# GEMM1 layer-0 row sum of squares via DPP moves instead of ds_bpermute; GEMM0 end-of-tile waits only on LDS
# speedup vs baseline: 1.0121x; 1.0121x over previous
; DI unsigned pk2(float lo, float hi) { f32x2 v = {lo, hi}; bfv2 b = __builtin_convertvector(v, bfv2); return __builtin_bit_cast(unsigned, b); }
; DI size_t tidxA(int row, int k) { return ((size_t)(row >> 8) * 32 + (k >> 5)) * 8192 + (size_t)(swz_chunk(row & 255, (k & 31) >> 3) * 8 + (k & 7)); }
; template <int MODE>
; DI void gemm_phase(const Params& p, int layer, unsigned char* lds) {
;     ...
;             const float* xr = layer == 0 ? (row < T_PROMPT ? p.x_prompt + (size_t)row * 1024 : p.x_sample + (size_t)(row - T_PROMPT) * 1024) : p.out + (size_t)row * 1024;
;             const f32x4 xv = *(const f32x4*)(xr + colg);
;             const f32x4 o = xv + cv;
;             *(f32x4*)(p.out + (size_t)row * 1024 + colg) = o;
;             if (layer == 0) {
;               *(u32x2*)(xb + tidxA(row, colg)) = (u32x2){pk2(o.x, o.y), pk2(o.z, o.w)};
;               float sq = o.x * o.x + o.y * o.y + o.z * o.z + o.w * o.w;
;               sq += __shfl_xor(sq, 1); sq += __shfl_xor(sq, 2); sq += __shfl_xor(sq, 4); sq += __shfl_xor(sq, 8);
;               if ((lane & 15) == 0) __hip_atomic_fetch_add(ssq + T_TOK + row, sq, __ATOMIC_RELAXED, __HIP_MEMORY_SCOPE_AGENT);
;             }
.Lg1r0k0_245:
	v_lshl_add_u64 v[74:75], v[134:135], 2, v[74:75]
	v_cndmask_b32_e64 v79, 0, 1, s[36:37]
	v_lshl_add_u64 v[72:73], v[68:69], 0, v[72:73]
	v_cmp_ne_u32_e64 s[40:41], 1, v79
	s_andn2_b64 vcc, exec, s[36:37]
	v_lshlrev_b32_e32 v79, 1, v154
	s_waitcnt vmcnt(15) lgkmcnt(0)
	v_pk_add_f32 v[66:67], v[66:67], v[90:91]
	v_pk_add_f32 v[64:65], v[64:65], v[88:89]
	global_store_dwordx4 v[72:73], v[64:67], off
	s_cbranch_vccnz .Lg1r0k0_249
	v_mul_f32_e32 v72, v65, v65
	v_fmac_f32_e32 v72, v64, v64
	v_cmp_lt_i32_e32 vcc, v185, v187
	v_fmac_f32_e32 v72, v66, v66
	v_fmac_f32_e32 v72, v67, v67
	v_cndmask_b32_e32 v73, v184, v185, vcc
	v_lshlrev_b32_e32 v73, 2, v73
	s_nop 1
	v_mov_b32_dpp v73, v72 quad_perm:[1,0,3,2] row_mask:0xf bank_mask:0xf
	v_cmp_lt_i32_e32 vcc, v188, v187
	v_xor_b32_e32 v74, 4, v184
	s_movk_i32 s2, 0x3cc
	s_waitcnt lgkmcnt(0)
	v_add_f32_e32 v72, v72, v73
	v_cndmask_b32_e32 v73, v184, v188, vcc
	v_lshlrev_b32_e32 v73, 2, v73
	s_nop 1
	v_mov_b32_dpp v73, v72 quad_perm:[2,3,0,1] row_mask:0xf bank_mask:0xf
	v_cmp_lt_i32_e32 vcc, v74, v187
	s_waitcnt lgkmcnt(0)
	v_add_f32_e32 v75, v72, v73
	v_cndmask_b32_e32 v72, v184, v74, vcc
	v_lshlrev_b32_e32 v72, 2, v72
	s_nop 1
	v_mov_b32_dpp v74, v75 row_half_mirror row_mask:0xf bank_mask:0xf
	v_cvt_pk_bf16_f32 v72, v64, v65
	v_xor_b32_e32 v65, 8, v184
	v_cmp_lt_i32_e32 vcc, v65, v187
	v_cvt_pk_bf16_f32 v73, v66, v67
	s_waitcnt lgkmcnt(0)
	v_add_f32_e32 v64, v75, v74
	v_cndmask_b32_e32 v65, v184, v65, vcc
	v_lshlrev_b32_e32 v65, 2, v65
	s_nop 1
	v_mov_b32_dpp v65, v64 row_mirror row_mask:0xf bank_mask:0xf
	v_add_u32_e32 v66, v165, v81
	v_and_or_b32 v66, v66, s2, v163
	v_lshl_or_b32 v160, v66, 4, v79
	v_lshl_add_u64 v[66:67], v[136:137], 0, v[160:161]
	global_store_dwordx2 v[66:67], v[72:73], off
	s_and_saveexec_b64 s[4:5], s[38:39]
	s_cbranch_execz .Lg1r0k0_248
	s_waitcnt lgkmcnt(0)
	v_add_f32_e32 v66, v64, v65
	v_lshl_add_u64 v[64:65], v[70:71], 2, s[24:25]
	global_atomic_add_f32 v[64:65], v66, off

; DI unsigned pk2(float lo, float hi) { f32x2 v = {lo, hi}; bfv2 b = __builtin_convertvector(v, bfv2); return __builtin_bit_cast(unsigned, b); }
; DI size_t tidxA(int row, int k) { return ((size_t)(row >> 8) * 32 + (k >> 5)) * 8192 + (size_t)(swz_chunk(row & 255, (k & 31) >> 3) * 8 + (k & 7)); }
; template <int MODE>
; DI void gemm_phase(const Params& p, int layer, unsigned char* lds) {
;     ...
;             const float* xr = layer == 0 ? (row < T_PROMPT ? p.x_prompt + (size_t)row * 1024 : p.x_sample + (size_t)(row - T_PROMPT) * 1024) : p.out + (size_t)row * 1024;
;             const f32x4 xv = *(const f32x4*)(xr + colg);
;             const f32x4 o = xv + cv;
;             *(f32x4*)(p.out + (size_t)row * 1024 + colg) = o;
;             if (layer == 0) {
;               *(u32x2*)(xb + tidxA(row, colg)) = (u32x2){pk2(o.x, o.y), pk2(o.z, o.w)};
;               float sq = o.x * o.x + o.y * o.y + o.z * o.z + o.w * o.w;
;               sq += __shfl_xor(sq, 1); sq += __shfl_xor(sq, 2); sq += __shfl_xor(sq, 4); sq += __shfl_xor(sq, 8);
;               if ((lane & 15) == 0) __hip_atomic_fetch_add(ssq + T_TOK + row, sq, __ATOMIC_RELAXED, __HIP_MEMORY_SCOPE_AGENT);
;             }
.Lg1r0k0_257:
	v_lshl_add_u64 v[76:77], v[134:135], 2, v[76:77]
	v_lshl_add_u64 v[74:75], v[68:69], 0, v[74:75]
	s_and_b64 vcc, exec, s[40:41]
	s_waitcnt vmcnt(15) lgkmcnt(0)
	v_pk_add_f32 v[66:67], v[66:67], v[94:95]
	v_pk_add_f32 v[64:65], v[64:65], v[92:93]
	global_store_dwordx4 v[74:75], v[64:67], off
	s_cbranch_vccnz .Lg1r0k0_261
	v_mul_f32_e32 v71, v65, v65
	v_fmac_f32_e32 v71, v64, v64
	v_cmp_lt_i32_e32 vcc, v185, v187
	v_fmac_f32_e32 v71, v66, v66
	v_fmac_f32_e32 v71, v67, v67
	v_cndmask_b32_e32 v74, v184, v185, vcc
	v_lshlrev_b32_e32 v74, 2, v74
	s_nop 1
	v_mov_b32_dpp v74, v71 quad_perm:[1,0,3,2] row_mask:0xf bank_mask:0xf
	v_cmp_lt_i32_e32 vcc, v188, v187
	s_waitcnt lgkmcnt(0)
	v_add_f32_e32 v71, v71, v74
	v_cndmask_b32_e32 v74, v184, v188, vcc
	v_lshlrev_b32_e32 v74, 2, v74
	s_nop 1
	v_mov_b32_dpp v75, v71 quad_perm:[2,3,0,1] row_mask:0xf bank_mask:0xf
	v_cvt_pk_bf16_f32 v74, v64, v65
	v_xor_b32_e32 v64, 4, v184
	v_cmp_lt_i32_e32 vcc, v64, v187
	s_waitcnt lgkmcnt(0)
	v_add_f32_e32 v65, v71, v75
	v_cndmask_b32_e32 v64, v184, v64, vcc
	v_lshlrev_b32_e32 v64, 2, v64
	s_nop 1
	v_mov_b32_dpp v64, v65 row_half_mirror row_mask:0xf bank_mask:0xf
	v_cvt_pk_bf16_f32 v75, v66, v67
	v_add3_u32 v66, v165, v81, 16
	v_and_or_b32 v66, v66, s82, v163
	v_lshlrev_b32_e32 v66, 3, v66
	s_waitcnt lgkmcnt(0)
	v_add_f32_e32 v64, v65, v64
	v_xor_b32_e32 v65, 8, v184
	v_cmp_lt_i32_e32 vcc, v65, v187
	v_bitop3_b32 v66, v66, 8, v154 bitop3:0x36
	v_lshlrev_b32_e32 v160, 1, v66
	v_cndmask_b32_e32 v65, v184, v65, vcc
	v_lshlrev_b32_e32 v65, 2, v65
	s_nop 1
	v_mov_b32_dpp v65, v64 row_mirror row_mask:0xf bank_mask:0xf
	v_lshl_add_u64 v[66:67], v[136:137], 0, v[160:161]
	global_store_dwordx2 v[66:67], v[74:75], off
	s_and_saveexec_b64 s[4:5], s[38:39]
	s_cbranch_execz .Lg1r0k0_260
	s_waitcnt lgkmcnt(0)
	v_add_f32_e32 v66, v64, v65
	v_lshl_add_u64 v[64:65], v[72:73], 2, s[24:25]
	global_atomic_add_f32 v[64:65], v66, off

; DI unsigned pk2(float lo, float hi) { f32x2 v = {lo, hi}; bfv2 b = __builtin_convertvector(v, bfv2); return __builtin_bit_cast(unsigned, b); }
; DI size_t tidxA(int row, int k) { return ((size_t)(row >> 8) * 32 + (k >> 5)) * 8192 + (size_t)(swz_chunk(row & 255, (k & 31) >> 3) * 8 + (k & 7)); }
; template <int MODE>
; DI void gemm_phase(const Params& p, int layer, unsigned char* lds) {
;     ...
;             const float* xr = layer == 0 ? (row < T_PROMPT ? p.x_prompt + (size_t)row * 1024 : p.x_sample + (size_t)(row - T_PROMPT) * 1024) : p.out + (size_t)row * 1024;
;             const f32x4 xv = *(const f32x4*)(xr + colg);
;             const f32x4 o = xv + cv;
;             *(f32x4*)(p.out + (size_t)row * 1024 + colg) = o;
;             if (layer == 0) {
;               *(u32x2*)(xb + tidxA(row, colg)) = (u32x2){pk2(o.x, o.y), pk2(o.z, o.w)};
;               float sq = o.x * o.x + o.y * o.y + o.z * o.z + o.w * o.w;
;               sq += __shfl_xor(sq, 1); sq += __shfl_xor(sq, 2); sq += __shfl_xor(sq, 4); sq += __shfl_xor(sq, 8);
;               if ((lane & 15) == 0) __hip_atomic_fetch_add(ssq + T_TOK + row, sq, __ATOMIC_RELAXED, __HIP_MEMORY_SCOPE_AGENT);
;             }
.Lg1r0k0_269:
	v_lshl_add_u64 v[76:77], v[134:135], 2, v[76:77]
	v_lshl_add_u64 v[74:75], v[68:69], 0, v[74:75]
	s_and_b64 vcc, exec, s[40:41]
	s_waitcnt vmcnt(15) lgkmcnt(0)
	v_pk_add_f32 v[66:67], v[66:67], v[98:99]
	v_pk_add_f32 v[64:65], v[64:65], v[96:97]
	global_store_dwordx4 v[74:75], v[64:67], off
	s_cbranch_vccnz .Lg1r0k0_273
	v_mul_f32_e32 v71, v65, v65
	v_fmac_f32_e32 v71, v64, v64
	v_cmp_lt_i32_e32 vcc, v185, v187
	v_fmac_f32_e32 v71, v66, v66
	v_fmac_f32_e32 v71, v67, v67
	v_cndmask_b32_e32 v74, v184, v185, vcc
	v_lshlrev_b32_e32 v74, 2, v74
	s_nop 1
	v_mov_b32_dpp v74, v71 quad_perm:[1,0,3,2] row_mask:0xf bank_mask:0xf
	v_cmp_lt_i32_e32 vcc, v188, v187
	s_waitcnt lgkmcnt(0)
	v_add_f32_e32 v71, v71, v74
	v_cndmask_b32_e32 v74, v184, v188, vcc
	v_lshlrev_b32_e32 v74, 2, v74
	s_nop 1
	v_mov_b32_dpp v75, v71 quad_perm:[2,3,0,1] row_mask:0xf bank_mask:0xf
	v_cvt_pk_bf16_f32 v74, v64, v65
	v_xor_b32_e32 v64, 4, v184
	v_cmp_lt_i32_e32 vcc, v64, v187
	s_waitcnt lgkmcnt(0)
	v_add_f32_e32 v65, v71, v75
	v_cndmask_b32_e32 v64, v184, v64, vcc
	v_lshlrev_b32_e32 v64, 2, v64
	s_nop 1
	v_mov_b32_dpp v64, v65 row_half_mirror row_mask:0xf bank_mask:0xf
	v_cvt_pk_bf16_f32 v75, v66, v67
	v_add3_u32 v66, v165, v81, 32
	v_and_or_b32 v66, v66, s82, v163
	v_lshlrev_b32_e32 v66, 3, v66
	s_waitcnt lgkmcnt(0)
	v_add_f32_e32 v64, v65, v64
	v_xor_b32_e32 v65, 8, v184
	v_cmp_lt_i32_e32 vcc, v65, v187
	v_bitop3_b32 v66, v66, 16, v154 bitop3:0x36
	v_lshlrev_b32_e32 v160, 1, v66
	v_cndmask_b32_e32 v65, v184, v65, vcc
	v_lshlrev_b32_e32 v65, 2, v65
	s_nop 1
	v_mov_b32_dpp v65, v64 row_mirror row_mask:0xf bank_mask:0xf
	v_lshl_add_u64 v[66:67], v[136:137], 0, v[160:161]
	global_store_dwordx2 v[66:67], v[74:75], off
	s_and_saveexec_b64 s[4:5], s[38:39]
	s_cbranch_execz .Lg1r0k0_272
	s_waitcnt lgkmcnt(0)
	v_add_f32_e32 v66, v64, v65
	v_lshl_add_u64 v[64:65], v[72:73], 2, s[24:25]
	global_atomic_add_f32 v[64:65], v66, off

; DI unsigned pk2(float lo, float hi) { f32x2 v = {lo, hi}; bfv2 b = __builtin_convertvector(v, bfv2); return __builtin_bit_cast(unsigned, b); }
; DI size_t tidxA(int row, int k) { return ((size_t)(row >> 8) * 32 + (k >> 5)) * 8192 + (size_t)(swz_chunk(row & 255, (k & 31) >> 3) * 8 + (k & 7)); }
; template <int MODE>
; DI void gemm_phase(const Params& p, int layer, unsigned char* lds) {
;     ...
;             const float* xr = layer == 0 ? (row < T_PROMPT ? p.x_prompt + (size_t)row * 1024 : p.x_sample + (size_t)(row - T_PROMPT) * 1024) : p.out + (size_t)row * 1024;
;             const f32x4 xv = *(const f32x4*)(xr + colg);
;             const f32x4 o = xv + cv;
;             *(f32x4*)(p.out + (size_t)row * 1024 + colg) = o;
;             if (layer == 0) {
;               *(u32x2*)(xb + tidxA(row, colg)) = (u32x2){pk2(o.x, o.y), pk2(o.z, o.w)};
;               float sq = o.x * o.x + o.y * o.y + o.z * o.z + o.w * o.w;
;               sq += __shfl_xor(sq, 1); sq += __shfl_xor(sq, 2); sq += __shfl_xor(sq, 4); sq += __shfl_xor(sq, 8);
;               if ((lane & 15) == 0) __hip_atomic_fetch_add(ssq + T_TOK + row, sq, __ATOMIC_RELAXED, __HIP_MEMORY_SCOPE_AGENT);
;             }
.Lg1r0k0_281:
	v_lshl_add_u64 v[70:71], v[134:135], 2, v[76:77]
	v_lshl_add_u64 v[70:71], v[68:69], 0, v[74:75]
	s_and_b64 vcc, exec, s[40:41]
	s_waitcnt vmcnt(15) lgkmcnt(0)
	v_pk_add_f32 v[66:67], v[66:67], v[102:103]
	v_pk_add_f32 v[64:65], v[64:65], v[100:101]
	global_store_dwordx4 v[70:71], v[64:67], off
	s_cbranch_vccnz .Lg1r0k0_236
	v_mul_f32_e32 v70, v65, v65
	v_fmac_f32_e32 v70, v64, v64
	v_cmp_lt_i32_e32 vcc, v185, v187
	v_fmac_f32_e32 v70, v66, v66
	v_fmac_f32_e32 v70, v67, v67
	v_cndmask_b32_e32 v71, v184, v185, vcc
	v_lshlrev_b32_e32 v71, 2, v71
	s_nop 1
	v_mov_b32_dpp v71, v70 quad_perm:[1,0,3,2] row_mask:0xf bank_mask:0xf
	v_cmp_lt_i32_e32 vcc, v188, v187
	s_waitcnt lgkmcnt(0)
	v_add_f32_e32 v71, v70, v71
	v_cndmask_b32_e32 v70, v184, v188, vcc
	v_lshlrev_b32_e32 v70, 2, v70
	s_nop 1
	v_mov_b32_dpp v74, v71 quad_perm:[2,3,0,1] row_mask:0xf bank_mask:0xf
	v_cvt_pk_bf16_f32 v70, v64, v65
	v_xor_b32_e32 v64, 4, v184
	v_cmp_lt_i32_e32 vcc, v64, v187
	s_waitcnt lgkmcnt(0)
	v_add_f32_e32 v65, v71, v74
	v_cndmask_b32_e32 v64, v184, v64, vcc
	v_lshlrev_b32_e32 v64, 2, v64
	s_nop 1
	v_mov_b32_dpp v64, v65 row_half_mirror row_mask:0xf bank_mask:0xf
	v_cvt_pk_bf16_f32 v71, v66, v67
	v_add3_u32 v66, v165, v81, 48
	v_and_or_b32 v66, v66, s82, v163
	v_lshlrev_b32_e32 v66, 3, v66
	s_waitcnt lgkmcnt(0)
	v_add_f32_e32 v64, v65, v64
	v_xor_b32_e32 v65, 8, v184
	v_cmp_lt_i32_e32 vcc, v65, v187
	v_bitop3_b32 v66, v66, 24, v154 bitop3:0x36
	v_lshlrev_b32_e32 v160, 1, v66
	v_cndmask_b32_e32 v65, v184, v65, vcc
	v_lshlrev_b32_e32 v65, 2, v65
	s_nop 1
	v_mov_b32_dpp v65, v64 row_mirror row_mask:0xf bank_mask:0xf
	v_lshl_add_u64 v[66:67], v[136:137], 0, v[160:161]
	global_store_dwordx2 v[66:67], v[70:71], off
	s_and_saveexec_b64 s[4:5], s[38:39]
	s_cbranch_execz .Lg1r0k0_235
	s_waitcnt lgkmcnt(0)
	v_add_f32_e32 v66, v64, v65
	v_lshl_add_u64 v[64:65], v[72:73], 2, s[24:25]
	global_atomic_add_f32 v[64:65], v66, off
	s_branch .Lg1r0k0_235

; DI unsigned pk2(float lo, float hi) { f32x2 v = {lo, hi}; bfv2 b = __builtin_convertvector(v, bfv2); return __builtin_bit_cast(unsigned, b); }
; DI size_t tidxA(int row, int k) { return ((size_t)(row >> 8) * 32 + (k >> 5)) * 8192 + (size_t)(swz_chunk(row & 255, (k & 31) >> 3) * 8 + (k & 7)); }
; template <int MODE>
; DI void gemm_phase(const Params& p, int layer, unsigned char* lds) {
;     ...
;             const float* xr = layer == 0 ? (row < T_PROMPT ? p.x_prompt + (size_t)row * 1024 : p.x_sample + (size_t)(row - T_PROMPT) * 1024) : p.out + (size_t)row * 1024;
;             const f32x4 xv = *(const f32x4*)(xr + colg);
;             const f32x4 o = xv + cv;
;             *(f32x4*)(p.out + (size_t)row * 1024 + colg) = o;
;             if (layer == 0) {
;               *(u32x2*)(xb + tidxA(row, colg)) = (u32x2){pk2(o.x, o.y), pk2(o.z, o.w)};
;               float sq = o.x * o.x + o.y * o.y + o.z * o.z + o.w * o.w;
;               sq += __shfl_xor(sq, 1); sq += __shfl_xor(sq, 2); sq += __shfl_xor(sq, 4); sq += __shfl_xor(sq, 8);
;               if ((lane & 15) == 0) __hip_atomic_fetch_add(ssq + T_TOK + row, sq, __ATOMIC_RELAXED, __HIP_MEMORY_SCOPE_AGENT);
;             }
.Lg1r0k1_245:
	v_lshl_add_u64 v[74:75], v[134:135], 2, v[74:75]
	v_cndmask_b32_e64 v79, 0, 1, s[36:37]
	v_lshl_add_u64 v[72:73], v[68:69], 0, v[72:73]
	v_cmp_ne_u32_e64 s[40:41], 1, v79
	s_andn2_b64 vcc, exec, s[36:37]
	v_lshlrev_b32_e32 v79, 1, v154
	s_waitcnt vmcnt(15) lgkmcnt(0)
	v_pk_add_f32 v[66:67], v[66:67], v[106:107]
	v_pk_add_f32 v[64:65], v[64:65], v[104:105]
	global_store_dwordx4 v[72:73], v[64:67], off
	s_cbranch_vccnz .Lg1r0k1_249
	v_mul_f32_e32 v72, v65, v65
	v_fmac_f32_e32 v72, v64, v64
	v_cmp_lt_i32_e32 vcc, v185, v187
	v_fmac_f32_e32 v72, v66, v66
	v_fmac_f32_e32 v72, v67, v67
	v_cndmask_b32_e32 v73, v184, v185, vcc
	v_lshlrev_b32_e32 v73, 2, v73
	s_nop 1
	v_mov_b32_dpp v73, v72 quad_perm:[1,0,3,2] row_mask:0xf bank_mask:0xf
	v_cmp_lt_i32_e32 vcc, v188, v187
	v_xor_b32_e32 v74, 4, v184
	s_movk_i32 s2, 0x3cc
	s_waitcnt lgkmcnt(0)
	v_add_f32_e32 v72, v72, v73
	v_cndmask_b32_e32 v73, v184, v188, vcc
	v_lshlrev_b32_e32 v73, 2, v73
	s_nop 1
	v_mov_b32_dpp v73, v72 quad_perm:[2,3,0,1] row_mask:0xf bank_mask:0xf
	v_cmp_lt_i32_e32 vcc, v74, v187
	s_waitcnt lgkmcnt(0)
	v_add_f32_e32 v75, v72, v73
	v_cndmask_b32_e32 v72, v184, v74, vcc
	v_lshlrev_b32_e32 v72, 2, v72
	s_nop 1
	v_mov_b32_dpp v74, v75 row_half_mirror row_mask:0xf bank_mask:0xf
	v_cvt_pk_bf16_f32 v72, v64, v65
	v_xor_b32_e32 v65, 8, v184
	v_cmp_lt_i32_e32 vcc, v65, v187
	v_cvt_pk_bf16_f32 v73, v66, v67
	s_waitcnt lgkmcnt(0)
	v_add_f32_e32 v64, v75, v74
	v_cndmask_b32_e32 v65, v184, v65, vcc
	v_lshlrev_b32_e32 v65, 2, v65
	s_nop 1
	v_mov_b32_dpp v65, v64 row_mirror row_mask:0xf bank_mask:0xf
	v_add_u32_e32 v66, v165, v81
	v_and_or_b32 v66, v66, s2, v163
	v_lshl_or_b32 v160, v66, 4, v79
	v_lshl_add_u64 v[66:67], v[136:137], 0, v[160:161]
	global_store_dwordx2 v[66:67], v[72:73], off
	s_and_saveexec_b64 s[4:5], s[38:39]
	s_cbranch_execz .Lg1r0k1_248
	s_waitcnt lgkmcnt(0)
	v_add_f32_e32 v66, v64, v65
	v_lshl_add_u64 v[64:65], v[70:71], 2, s[24:25]
	global_atomic_add_f32 v[64:65], v66, off

; DI unsigned pk2(float lo, float hi) { f32x2 v = {lo, hi}; bfv2 b = __builtin_convertvector(v, bfv2); return __builtin_bit_cast(unsigned, b); }
; DI size_t tidxA(int row, int k) { return ((size_t)(row >> 8) * 32 + (k >> 5)) * 8192 + (size_t)(swz_chunk(row & 255, (k & 31) >> 3) * 8 + (k & 7)); }
; template <int MODE>
; DI void gemm_phase(const Params& p, int layer, unsigned char* lds) {
;     ...
;             const float* xr = layer == 0 ? (row < T_PROMPT ? p.x_prompt + (size_t)row * 1024 : p.x_sample + (size_t)(row - T_PROMPT) * 1024) : p.out + (size_t)row * 1024;
;             const f32x4 xv = *(const f32x4*)(xr + colg);
;             const f32x4 o = xv + cv;
;             *(f32x4*)(p.out + (size_t)row * 1024 + colg) = o;
;             if (layer == 0) {
;               *(u32x2*)(xb + tidxA(row, colg)) = (u32x2){pk2(o.x, o.y), pk2(o.z, o.w)};
;               float sq = o.x * o.x + o.y * o.y + o.z * o.z + o.w * o.w;
;               sq += __shfl_xor(sq, 1); sq += __shfl_xor(sq, 2); sq += __shfl_xor(sq, 4); sq += __shfl_xor(sq, 8);
;               if ((lane & 15) == 0) __hip_atomic_fetch_add(ssq + T_TOK + row, sq, __ATOMIC_RELAXED, __HIP_MEMORY_SCOPE_AGENT);
;             }
.Lg1r0k1_257:
	v_lshl_add_u64 v[76:77], v[134:135], 2, v[76:77]
	v_lshl_add_u64 v[74:75], v[68:69], 0, v[74:75]
	s_and_b64 vcc, exec, s[40:41]
	s_waitcnt vmcnt(15) lgkmcnt(0)
	v_pk_add_f32 v[66:67], v[66:67], v[110:111]
	v_pk_add_f32 v[64:65], v[64:65], v[108:109]
	global_store_dwordx4 v[74:75], v[64:67], off
	s_cbranch_vccnz .Lg1r0k1_261
	v_mul_f32_e32 v71, v65, v65
	v_fmac_f32_e32 v71, v64, v64
	v_cmp_lt_i32_e32 vcc, v185, v187
	v_fmac_f32_e32 v71, v66, v66
	v_fmac_f32_e32 v71, v67, v67
	v_cndmask_b32_e32 v74, v184, v185, vcc
	v_lshlrev_b32_e32 v74, 2, v74
	s_nop 1
	v_mov_b32_dpp v74, v71 quad_perm:[1,0,3,2] row_mask:0xf bank_mask:0xf
	v_cmp_lt_i32_e32 vcc, v188, v187
	s_waitcnt lgkmcnt(0)
	v_add_f32_e32 v71, v71, v74
	v_cndmask_b32_e32 v74, v184, v188, vcc
	v_lshlrev_b32_e32 v74, 2, v74
	s_nop 1
	v_mov_b32_dpp v75, v71 quad_perm:[2,3,0,1] row_mask:0xf bank_mask:0xf
	v_cvt_pk_bf16_f32 v74, v64, v65
	v_xor_b32_e32 v64, 4, v184
	v_cmp_lt_i32_e32 vcc, v64, v187
	s_waitcnt lgkmcnt(0)
	v_add_f32_e32 v65, v71, v75
	v_cndmask_b32_e32 v64, v184, v64, vcc
	v_lshlrev_b32_e32 v64, 2, v64
	s_nop 1
	v_mov_b32_dpp v64, v65 row_half_mirror row_mask:0xf bank_mask:0xf
	v_cvt_pk_bf16_f32 v75, v66, v67
	v_add3_u32 v66, v165, v81, 16
	v_and_or_b32 v66, v66, s82, v163
	v_lshlrev_b32_e32 v66, 3, v66
	s_waitcnt lgkmcnt(0)
	v_add_f32_e32 v64, v65, v64
	v_xor_b32_e32 v65, 8, v184
	v_cmp_lt_i32_e32 vcc, v65, v187
	v_bitop3_b32 v66, v66, 8, v154 bitop3:0x36
	v_lshlrev_b32_e32 v160, 1, v66
	v_cndmask_b32_e32 v65, v184, v65, vcc
	v_lshlrev_b32_e32 v65, 2, v65
	s_nop 1
	v_mov_b32_dpp v65, v64 row_mirror row_mask:0xf bank_mask:0xf
	v_lshl_add_u64 v[66:67], v[136:137], 0, v[160:161]
	global_store_dwordx2 v[66:67], v[74:75], off
	s_and_saveexec_b64 s[4:5], s[38:39]
	s_cbranch_execz .Lg1r0k1_260
	s_waitcnt lgkmcnt(0)
	v_add_f32_e32 v66, v64, v65
	v_lshl_add_u64 v[64:65], v[72:73], 2, s[24:25]
	global_atomic_add_f32 v[64:65], v66, off

; DI unsigned pk2(float lo, float hi) { f32x2 v = {lo, hi}; bfv2 b = __builtin_convertvector(v, bfv2); return __builtin_bit_cast(unsigned, b); }
; DI size_t tidxA(int row, int k) { return ((size_t)(row >> 8) * 32 + (k >> 5)) * 8192 + (size_t)(swz_chunk(row & 255, (k & 31) >> 3) * 8 + (k & 7)); }
; template <int MODE>
; DI void gemm_phase(const Params& p, int layer, unsigned char* lds) {
;     ...
;             const float* xr = layer == 0 ? (row < T_PROMPT ? p.x_prompt + (size_t)row * 1024 : p.x_sample + (size_t)(row - T_PROMPT) * 1024) : p.out + (size_t)row * 1024;
;             const f32x4 xv = *(const f32x4*)(xr + colg);
;             const f32x4 o = xv + cv;
;             *(f32x4*)(p.out + (size_t)row * 1024 + colg) = o;
;             if (layer == 0) {
;               *(u32x2*)(xb + tidxA(row, colg)) = (u32x2){pk2(o.x, o.y), pk2(o.z, o.w)};
;               float sq = o.x * o.x + o.y * o.y + o.z * o.z + o.w * o.w;
;               sq += __shfl_xor(sq, 1); sq += __shfl_xor(sq, 2); sq += __shfl_xor(sq, 4); sq += __shfl_xor(sq, 8);
;               if ((lane & 15) == 0) __hip_atomic_fetch_add(ssq + T_TOK + row, sq, __ATOMIC_RELAXED, __HIP_MEMORY_SCOPE_AGENT);
;             }
.Lg1r0k1_269:
	v_lshl_add_u64 v[76:77], v[134:135], 2, v[76:77]
	v_lshl_add_u64 v[74:75], v[68:69], 0, v[74:75]
	s_and_b64 vcc, exec, s[40:41]
	s_waitcnt vmcnt(15) lgkmcnt(0)
	v_pk_add_f32 v[66:67], v[66:67], v[114:115]
	v_pk_add_f32 v[64:65], v[64:65], v[112:113]
	global_store_dwordx4 v[74:75], v[64:67], off
	s_cbranch_vccnz .Lg1r0k1_273
	v_mul_f32_e32 v71, v65, v65
	v_fmac_f32_e32 v71, v64, v64
	v_cmp_lt_i32_e32 vcc, v185, v187
	v_fmac_f32_e32 v71, v66, v66
	v_fmac_f32_e32 v71, v67, v67
	v_cndmask_b32_e32 v74, v184, v185, vcc
	v_lshlrev_b32_e32 v74, 2, v74
	s_nop 1
	v_mov_b32_dpp v74, v71 quad_perm:[1,0,3,2] row_mask:0xf bank_mask:0xf
	v_cmp_lt_i32_e32 vcc, v188, v187
	s_waitcnt lgkmcnt(0)
	v_add_f32_e32 v71, v71, v74
	v_cndmask_b32_e32 v74, v184, v188, vcc
	v_lshlrev_b32_e32 v74, 2, v74
	s_nop 1
	v_mov_b32_dpp v75, v71 quad_perm:[2,3,0,1] row_mask:0xf bank_mask:0xf
	v_cvt_pk_bf16_f32 v74, v64, v65
	v_xor_b32_e32 v64, 4, v184
	v_cmp_lt_i32_e32 vcc, v64, v187
	s_waitcnt lgkmcnt(0)
	v_add_f32_e32 v65, v71, v75
	v_cndmask_b32_e32 v64, v184, v64, vcc
	v_lshlrev_b32_e32 v64, 2, v64
	s_nop 1
	v_mov_b32_dpp v64, v65 row_half_mirror row_mask:0xf bank_mask:0xf
	v_cvt_pk_bf16_f32 v75, v66, v67
	v_add3_u32 v66, v165, v81, 32
	v_and_or_b32 v66, v66, s82, v163
	v_lshlrev_b32_e32 v66, 3, v66
	s_waitcnt lgkmcnt(0)
	v_add_f32_e32 v64, v65, v64
	v_xor_b32_e32 v65, 8, v184
	v_cmp_lt_i32_e32 vcc, v65, v187
	v_bitop3_b32 v66, v66, 16, v154 bitop3:0x36
	v_lshlrev_b32_e32 v160, 1, v66
	v_cndmask_b32_e32 v65, v184, v65, vcc
	v_lshlrev_b32_e32 v65, 2, v65
	s_nop 1
	v_mov_b32_dpp v65, v64 row_mirror row_mask:0xf bank_mask:0xf
	v_lshl_add_u64 v[66:67], v[136:137], 0, v[160:161]
	global_store_dwordx2 v[66:67], v[74:75], off
	s_and_saveexec_b64 s[4:5], s[38:39]
	s_cbranch_execz .Lg1r0k1_272
	s_waitcnt lgkmcnt(0)
	v_add_f32_e32 v66, v64, v65
	v_lshl_add_u64 v[64:65], v[72:73], 2, s[24:25]
	global_atomic_add_f32 v[64:65], v66, off

; DI unsigned pk2(float lo, float hi) { f32x2 v = {lo, hi}; bfv2 b = __builtin_convertvector(v, bfv2); return __builtin_bit_cast(unsigned, b); }
; DI size_t tidxA(int row, int k) { return ((size_t)(row >> 8) * 32 + (k >> 5)) * 8192 + (size_t)(swz_chunk(row & 255, (k & 31) >> 3) * 8 + (k & 7)); }
; template <int MODE>
; DI void gemm_phase(const Params& p, int layer, unsigned char* lds) {
;     ...
;             const float* xr = layer == 0 ? (row < T_PROMPT ? p.x_prompt + (size_t)row * 1024 : p.x_sample + (size_t)(row - T_PROMPT) * 1024) : p.out + (size_t)row * 1024;
;             const f32x4 xv = *(const f32x4*)(xr + colg);
;             const f32x4 o = xv + cv;
;             *(f32x4*)(p.out + (size_t)row * 1024 + colg) = o;
;             if (layer == 0) {
;               *(u32x2*)(xb + tidxA(row, colg)) = (u32x2){pk2(o.x, o.y), pk2(o.z, o.w)};
;               float sq = o.x * o.x + o.y * o.y + o.z * o.z + o.w * o.w;
;               sq += __shfl_xor(sq, 1); sq += __shfl_xor(sq, 2); sq += __shfl_xor(sq, 4); sq += __shfl_xor(sq, 8);
;               if ((lane & 15) == 0) __hip_atomic_fetch_add(ssq + T_TOK + row, sq, __ATOMIC_RELAXED, __HIP_MEMORY_SCOPE_AGENT);
;             }
.Lg1r0k1_281:
	v_lshl_add_u64 v[70:71], v[134:135], 2, v[76:77]
	v_lshl_add_u64 v[70:71], v[68:69], 0, v[74:75]
	s_and_b64 vcc, exec, s[40:41]
	s_waitcnt vmcnt(15) lgkmcnt(0)
	v_pk_add_f32 v[66:67], v[66:67], v[118:119]
	v_pk_add_f32 v[64:65], v[64:65], v[116:117]
	global_store_dwordx4 v[70:71], v[64:67], off
	s_cbranch_vccnz .Lg1r0k1_236
	v_mul_f32_e32 v70, v65, v65
	v_fmac_f32_e32 v70, v64, v64
	v_cmp_lt_i32_e32 vcc, v185, v187
	v_fmac_f32_e32 v70, v66, v66
	v_fmac_f32_e32 v70, v67, v67
	v_cndmask_b32_e32 v71, v184, v185, vcc
	v_lshlrev_b32_e32 v71, 2, v71
	s_nop 1
	v_mov_b32_dpp v71, v70 quad_perm:[1,0,3,2] row_mask:0xf bank_mask:0xf
	v_cmp_lt_i32_e32 vcc, v188, v187
	s_waitcnt lgkmcnt(0)
	v_add_f32_e32 v71, v70, v71
	v_cndmask_b32_e32 v70, v184, v188, vcc
	v_lshlrev_b32_e32 v70, 2, v70
	s_nop 1
	v_mov_b32_dpp v74, v71 quad_perm:[2,3,0,1] row_mask:0xf bank_mask:0xf
	v_cvt_pk_bf16_f32 v70, v64, v65
	v_xor_b32_e32 v64, 4, v184
	v_cmp_lt_i32_e32 vcc, v64, v187
	s_waitcnt lgkmcnt(0)
	v_add_f32_e32 v65, v71, v74
	v_cndmask_b32_e32 v64, v184, v64, vcc
	v_lshlrev_b32_e32 v64, 2, v64
	s_nop 1
	v_mov_b32_dpp v64, v65 row_half_mirror row_mask:0xf bank_mask:0xf
	v_cvt_pk_bf16_f32 v71, v66, v67
	v_add3_u32 v66, v165, v81, 48
	v_and_or_b32 v66, v66, s82, v163
	v_lshlrev_b32_e32 v66, 3, v66
	s_waitcnt lgkmcnt(0)
	v_add_f32_e32 v64, v65, v64
	v_xor_b32_e32 v65, 8, v184
	v_cmp_lt_i32_e32 vcc, v65, v187
	v_bitop3_b32 v66, v66, 24, v154 bitop3:0x36
	v_lshlrev_b32_e32 v160, 1, v66
	v_cndmask_b32_e32 v65, v184, v65, vcc
	v_lshlrev_b32_e32 v65, 2, v65
	s_nop 1
	v_mov_b32_dpp v65, v64 row_mirror row_mask:0xf bank_mask:0xf
	v_lshl_add_u64 v[66:67], v[136:137], 0, v[160:161]
	global_store_dwordx2 v[66:67], v[70:71], off
	s_and_saveexec_b64 s[4:5], s[38:39]
	s_cbranch_execz .Lg1r0k1_235
	s_waitcnt lgkmcnt(0)
	v_add_f32_e32 v66, v64, v65
	v_lshl_add_u64 v[64:65], v[72:73], 2, s[24:25]
	global_atomic_add_f32 v[64:65], v66, off
	s_branch .Lg1r0k1_235

; DI unsigned pk2(float lo, float hi) { f32x2 v = {lo, hi}; bfv2 b = __builtin_convertvector(v, bfv2); return __builtin_bit_cast(unsigned, b); }
; DI size_t tidxA(int row, int k) { return ((size_t)(row >> 8) * 32 + (k >> 5)) * 8192 + (size_t)(swz_chunk(row & 255, (k & 31) >> 3) * 8 + (k & 7)); }
; template <int MODE>
; DI void gemm_phase(const Params& p, int layer, unsigned char* lds) {
;     ...
;             const float* xr = layer == 0 ? (row < T_PROMPT ? p.x_prompt + (size_t)row * 1024 : p.x_sample + (size_t)(row - T_PROMPT) * 1024) : p.out + (size_t)row * 1024;
;             const f32x4 xv = *(const f32x4*)(xr + colg);
;             const f32x4 o = xv + cv;
;             *(f32x4*)(p.out + (size_t)row * 1024 + colg) = o;
;             if (layer == 0) {
;               *(u32x2*)(xb + tidxA(row, colg)) = (u32x2){pk2(o.x, o.y), pk2(o.z, o.w)};
;               float sq = o.x * o.x + o.y * o.y + o.z * o.z + o.w * o.w;
;               sq += __shfl_xor(sq, 1); sq += __shfl_xor(sq, 2); sq += __shfl_xor(sq, 4); sq += __shfl_xor(sq, 8);
;               if ((lane & 15) == 0) __hip_atomic_fetch_add(ssq + T_TOK + row, sq, __ATOMIC_RELAXED, __HIP_MEMORY_SCOPE_AGENT);
;             }
.Lg1r0k2_245:
	v_lshl_add_u64 v[74:75], v[134:135], 2, v[74:75]
	v_cndmask_b32_e64 v79, 0, 1, s[36:37]
	v_lshl_add_u64 v[72:73], v[68:69], 0, v[72:73]
	v_cmp_ne_u32_e64 s[40:41], 1, v79
	s_andn2_b64 vcc, exec, s[36:37]
	v_lshlrev_b32_e32 v79, 1, v154
	s_waitcnt vmcnt(15) lgkmcnt(0)
	v_pk_add_f32 v[66:67], v[66:67], v[122:123]
	v_pk_add_f32 v[64:65], v[64:65], v[120:121]
	global_store_dwordx4 v[72:73], v[64:67], off
	s_cbranch_vccnz .Lg1r0k2_249
	v_mul_f32_e32 v72, v65, v65
	v_fmac_f32_e32 v72, v64, v64
	v_cmp_lt_i32_e32 vcc, v185, v187
	v_fmac_f32_e32 v72, v66, v66
	v_fmac_f32_e32 v72, v67, v67
	v_cndmask_b32_e32 v73, v184, v185, vcc
	v_lshlrev_b32_e32 v73, 2, v73
	s_nop 1
	v_mov_b32_dpp v73, v72 quad_perm:[1,0,3,2] row_mask:0xf bank_mask:0xf
	v_cmp_lt_i32_e32 vcc, v188, v187
	v_xor_b32_e32 v74, 4, v184
	s_movk_i32 s2, 0x3cc
	s_waitcnt lgkmcnt(0)
	v_add_f32_e32 v72, v72, v73
	v_cndmask_b32_e32 v73, v184, v188, vcc
	v_lshlrev_b32_e32 v73, 2, v73
	s_nop 1
	v_mov_b32_dpp v73, v72 quad_perm:[2,3,0,1] row_mask:0xf bank_mask:0xf
	v_cmp_lt_i32_e32 vcc, v74, v187
	s_waitcnt lgkmcnt(0)
	v_add_f32_e32 v75, v72, v73
	v_cndmask_b32_e32 v72, v184, v74, vcc
	v_lshlrev_b32_e32 v72, 2, v72
	s_nop 1
	v_mov_b32_dpp v74, v75 row_half_mirror row_mask:0xf bank_mask:0xf
	v_cvt_pk_bf16_f32 v72, v64, v65
	v_xor_b32_e32 v65, 8, v184
	v_cmp_lt_i32_e32 vcc, v65, v187
	v_cvt_pk_bf16_f32 v73, v66, v67
	s_waitcnt lgkmcnt(0)
	v_add_f32_e32 v64, v75, v74
	v_cndmask_b32_e32 v65, v184, v65, vcc
	v_lshlrev_b32_e32 v65, 2, v65
	s_nop 1
	v_mov_b32_dpp v65, v64 row_mirror row_mask:0xf bank_mask:0xf
	v_add_u32_e32 v66, v165, v81
	v_and_or_b32 v66, v66, s2, v163
	v_lshl_or_b32 v160, v66, 4, v79
	v_lshl_add_u64 v[66:67], v[136:137], 0, v[160:161]
	global_store_dwordx2 v[66:67], v[72:73], off
	s_and_saveexec_b64 s[4:5], s[38:39]
	s_cbranch_execz .Lg1r0k2_248
	s_waitcnt lgkmcnt(0)
	v_add_f32_e32 v66, v64, v65
	v_lshl_add_u64 v[64:65], v[70:71], 2, s[24:25]
	global_atomic_add_f32 v[64:65], v66, off

; DI unsigned pk2(float lo, float hi) { f32x2 v = {lo, hi}; bfv2 b = __builtin_convertvector(v, bfv2); return __builtin_bit_cast(unsigned, b); }
; DI size_t tidxA(int row, int k) { return ((size_t)(row >> 8) * 32 + (k >> 5)) * 8192 + (size_t)(swz_chunk(row & 255, (k & 31) >> 3) * 8 + (k & 7)); }
; template <int MODE>
; DI void gemm_phase(const Params& p, int layer, unsigned char* lds) {
;     ...
;             const float* xr = layer == 0 ? (row < T_PROMPT ? p.x_prompt + (size_t)row * 1024 : p.x_sample + (size_t)(row - T_PROMPT) * 1024) : p.out + (size_t)row * 1024;
;             const f32x4 xv = *(const f32x4*)(xr + colg);
;             const f32x4 o = xv + cv;
;             *(f32x4*)(p.out + (size_t)row * 1024 + colg) = o;
;             if (layer == 0) {
;               *(u32x2*)(xb + tidxA(row, colg)) = (u32x2){pk2(o.x, o.y), pk2(o.z, o.w)};
;               float sq = o.x * o.x + o.y * o.y + o.z * o.z + o.w * o.w;
;               sq += __shfl_xor(sq, 1); sq += __shfl_xor(sq, 2); sq += __shfl_xor(sq, 4); sq += __shfl_xor(sq, 8);
;               if ((lane & 15) == 0) __hip_atomic_fetch_add(ssq + T_TOK + row, sq, __ATOMIC_RELAXED, __HIP_MEMORY_SCOPE_AGENT);
;             }
.Lg1r0k2_257:
	v_lshl_add_u64 v[76:77], v[134:135], 2, v[76:77]
	v_lshl_add_u64 v[74:75], v[68:69], 0, v[74:75]
	s_and_b64 vcc, exec, s[40:41]
	s_waitcnt vmcnt(15) lgkmcnt(0)
	v_pk_add_f32 v[66:67], v[66:67], v[126:127]
	v_pk_add_f32 v[64:65], v[64:65], v[124:125]
	global_store_dwordx4 v[74:75], v[64:67], off
	s_cbranch_vccnz .Lg1r0k2_261
	v_mul_f32_e32 v71, v65, v65
	v_fmac_f32_e32 v71, v64, v64
	v_cmp_lt_i32_e32 vcc, v185, v187
	v_fmac_f32_e32 v71, v66, v66
	v_fmac_f32_e32 v71, v67, v67
	v_cndmask_b32_e32 v74, v184, v185, vcc
	v_lshlrev_b32_e32 v74, 2, v74
	s_nop 1
	v_mov_b32_dpp v74, v71 quad_perm:[1,0,3,2] row_mask:0xf bank_mask:0xf
	v_cmp_lt_i32_e32 vcc, v188, v187
	s_waitcnt lgkmcnt(0)
	v_add_f32_e32 v71, v71, v74
	v_cndmask_b32_e32 v74, v184, v188, vcc
	v_lshlrev_b32_e32 v74, 2, v74
	s_nop 1
	v_mov_b32_dpp v75, v71 quad_perm:[2,3,0,1] row_mask:0xf bank_mask:0xf
	v_cvt_pk_bf16_f32 v74, v64, v65
	v_xor_b32_e32 v64, 4, v184
	v_cmp_lt_i32_e32 vcc, v64, v187
	s_waitcnt lgkmcnt(0)
	v_add_f32_e32 v65, v71, v75
	v_cndmask_b32_e32 v64, v184, v64, vcc
	v_lshlrev_b32_e32 v64, 2, v64
	s_nop 1
	v_mov_b32_dpp v64, v65 row_half_mirror row_mask:0xf bank_mask:0xf
	v_cvt_pk_bf16_f32 v75, v66, v67
	v_add3_u32 v66, v165, v81, 16
	v_and_or_b32 v66, v66, s82, v163
	v_lshlrev_b32_e32 v66, 3, v66
	s_waitcnt lgkmcnt(0)
	v_add_f32_e32 v64, v65, v64
	v_xor_b32_e32 v65, 8, v184
	v_cmp_lt_i32_e32 vcc, v65, v187
	v_bitop3_b32 v66, v66, 8, v154 bitop3:0x36
	v_lshlrev_b32_e32 v160, 1, v66
	v_cndmask_b32_e32 v65, v184, v65, vcc
	v_lshlrev_b32_e32 v65, 2, v65
	s_nop 1
	v_mov_b32_dpp v65, v64 row_mirror row_mask:0xf bank_mask:0xf
	v_lshl_add_u64 v[66:67], v[136:137], 0, v[160:161]
	global_store_dwordx2 v[66:67], v[74:75], off
	s_and_saveexec_b64 s[4:5], s[38:39]
	s_cbranch_execz .Lg1r0k2_260
	s_waitcnt lgkmcnt(0)
	v_add_f32_e32 v66, v64, v65
	v_lshl_add_u64 v[64:65], v[72:73], 2, s[24:25]
	global_atomic_add_f32 v[64:65], v66, off

; DI unsigned pk2(float lo, float hi) { f32x2 v = {lo, hi}; bfv2 b = __builtin_convertvector(v, bfv2); return __builtin_bit_cast(unsigned, b); }
; DI size_t tidxA(int row, int k) { return ((size_t)(row >> 8) * 32 + (k >> 5)) * 8192 + (size_t)(swz_chunk(row & 255, (k & 31) >> 3) * 8 + (k & 7)); }
; template <int MODE>
; DI void gemm_phase(const Params& p, int layer, unsigned char* lds) {
;     ...
;             const float* xr = layer == 0 ? (row < T_PROMPT ? p.x_prompt + (size_t)row * 1024 : p.x_sample + (size_t)(row - T_PROMPT) * 1024) : p.out + (size_t)row * 1024;
;             const f32x4 xv = *(const f32x4*)(xr + colg);
;             const f32x4 o = xv + cv;
;             *(f32x4*)(p.out + (size_t)row * 1024 + colg) = o;
;             if (layer == 0) {
;               *(u32x2*)(xb + tidxA(row, colg)) = (u32x2){pk2(o.x, o.y), pk2(o.z, o.w)};
;               float sq = o.x * o.x + o.y * o.y + o.z * o.z + o.w * o.w;
;               sq += __shfl_xor(sq, 1); sq += __shfl_xor(sq, 2); sq += __shfl_xor(sq, 4); sq += __shfl_xor(sq, 8);
;               if ((lane & 15) == 0) __hip_atomic_fetch_add(ssq + T_TOK + row, sq, __ATOMIC_RELAXED, __HIP_MEMORY_SCOPE_AGENT);
;             }
.Lg1r0k2_269:
	v_lshl_add_u64 v[76:77], v[134:135], 2, v[76:77]
	v_lshl_add_u64 v[74:75], v[68:69], 0, v[74:75]
	s_and_b64 vcc, exec, s[40:41]
	s_waitcnt vmcnt(15) lgkmcnt(0)
	v_pk_add_f32 v[66:67], v[66:67], v[206:207]
	v_pk_add_f32 v[64:65], v[64:65], v[204:205]
	global_store_dwordx4 v[74:75], v[64:67], off
	s_cbranch_vccnz .Lg1r0k2_273
	v_mul_f32_e32 v71, v65, v65
	v_fmac_f32_e32 v71, v64, v64
	v_cmp_lt_i32_e32 vcc, v185, v187
	v_fmac_f32_e32 v71, v66, v66
	v_fmac_f32_e32 v71, v67, v67
	v_cndmask_b32_e32 v74, v184, v185, vcc
	v_lshlrev_b32_e32 v74, 2, v74
	s_nop 1
	v_mov_b32_dpp v74, v71 quad_perm:[1,0,3,2] row_mask:0xf bank_mask:0xf
	v_cmp_lt_i32_e32 vcc, v188, v187
	s_waitcnt lgkmcnt(0)
	v_add_f32_e32 v71, v71, v74
	v_cndmask_b32_e32 v74, v184, v188, vcc
	v_lshlrev_b32_e32 v74, 2, v74
	s_nop 1
	v_mov_b32_dpp v75, v71 quad_perm:[2,3,0,1] row_mask:0xf bank_mask:0xf
	v_cvt_pk_bf16_f32 v74, v64, v65
	v_xor_b32_e32 v64, 4, v184
	v_cmp_lt_i32_e32 vcc, v64, v187
	s_waitcnt lgkmcnt(0)
	v_add_f32_e32 v65, v71, v75
	v_cndmask_b32_e32 v64, v184, v64, vcc
	v_lshlrev_b32_e32 v64, 2, v64
	s_nop 1
	v_mov_b32_dpp v64, v65 row_half_mirror row_mask:0xf bank_mask:0xf
	v_cvt_pk_bf16_f32 v75, v66, v67
	v_add3_u32 v66, v165, v81, 32
	v_and_or_b32 v66, v66, s82, v163
	v_lshlrev_b32_e32 v66, 3, v66
	s_waitcnt lgkmcnt(0)
	v_add_f32_e32 v64, v65, v64
	v_xor_b32_e32 v65, 8, v184
	v_cmp_lt_i32_e32 vcc, v65, v187
	v_bitop3_b32 v66, v66, 16, v154 bitop3:0x36
	v_lshlrev_b32_e32 v160, 1, v66
	v_cndmask_b32_e32 v65, v184, v65, vcc
	v_lshlrev_b32_e32 v65, 2, v65
	s_nop 1
	v_mov_b32_dpp v65, v64 row_mirror row_mask:0xf bank_mask:0xf
	v_lshl_add_u64 v[66:67], v[136:137], 0, v[160:161]
	global_store_dwordx2 v[66:67], v[74:75], off
	s_and_saveexec_b64 s[4:5], s[38:39]
	s_cbranch_execz .Lg1r0k2_272
	s_waitcnt lgkmcnt(0)
	v_add_f32_e32 v66, v64, v65
	v_lshl_add_u64 v[64:65], v[72:73], 2, s[24:25]
	global_atomic_add_f32 v[64:65], v66, off

; DI unsigned pk2(float lo, float hi) { f32x2 v = {lo, hi}; bfv2 b = __builtin_convertvector(v, bfv2); return __builtin_bit_cast(unsigned, b); }
; DI size_t tidxA(int row, int k) { return ((size_t)(row >> 8) * 32 + (k >> 5)) * 8192 + (size_t)(swz_chunk(row & 255, (k & 31) >> 3) * 8 + (k & 7)); }
; template <int MODE>
; DI void gemm_phase(const Params& p, int layer, unsigned char* lds) {
;     ...
;             const float* xr = layer == 0 ? (row < T_PROMPT ? p.x_prompt + (size_t)row * 1024 : p.x_sample + (size_t)(row - T_PROMPT) * 1024) : p.out + (size_t)row * 1024;
;             const f32x4 xv = *(const f32x4*)(xr + colg);
;             const f32x4 o = xv + cv;
;             *(f32x4*)(p.out + (size_t)row * 1024 + colg) = o;
;             if (layer == 0) {
;               *(u32x2*)(xb + tidxA(row, colg)) = (u32x2){pk2(o.x, o.y), pk2(o.z, o.w)};
;               float sq = o.x * o.x + o.y * o.y + o.z * o.z + o.w * o.w;
;               sq += __shfl_xor(sq, 1); sq += __shfl_xor(sq, 2); sq += __shfl_xor(sq, 4); sq += __shfl_xor(sq, 8);
;               if ((lane & 15) == 0) __hip_atomic_fetch_add(ssq + T_TOK + row, sq, __ATOMIC_RELAXED, __HIP_MEMORY_SCOPE_AGENT);
;             }
.Lg1r0k2_281:
	v_lshl_add_u64 v[70:71], v[134:135], 2, v[76:77]
	v_lshl_add_u64 v[70:71], v[68:69], 0, v[74:75]
	s_and_b64 vcc, exec, s[40:41]
	s_waitcnt vmcnt(15) lgkmcnt(0)
	v_pk_add_f32 v[66:67], v[66:67], v[210:211]
	v_pk_add_f32 v[64:65], v[64:65], v[208:209]
	global_store_dwordx4 v[70:71], v[64:67], off
	s_cbranch_vccnz .Lg1r0k2_236
	v_mul_f32_e32 v70, v65, v65
	v_fmac_f32_e32 v70, v64, v64
	v_cmp_lt_i32_e32 vcc, v185, v187
	v_fmac_f32_e32 v70, v66, v66
	v_fmac_f32_e32 v70, v67, v67
	v_cndmask_b32_e32 v71, v184, v185, vcc
	v_lshlrev_b32_e32 v71, 2, v71
	s_nop 1
	v_mov_b32_dpp v71, v70 quad_perm:[1,0,3,2] row_mask:0xf bank_mask:0xf
	v_cmp_lt_i32_e32 vcc, v188, v187
	s_waitcnt lgkmcnt(0)
	v_add_f32_e32 v71, v70, v71
	v_cndmask_b32_e32 v70, v184, v188, vcc
	v_lshlrev_b32_e32 v70, 2, v70
	s_nop 1
	v_mov_b32_dpp v74, v71 quad_perm:[2,3,0,1] row_mask:0xf bank_mask:0xf
	v_cvt_pk_bf16_f32 v70, v64, v65
	v_xor_b32_e32 v64, 4, v184
	v_cmp_lt_i32_e32 vcc, v64, v187
	s_waitcnt lgkmcnt(0)
	v_add_f32_e32 v65, v71, v74
	v_cndmask_b32_e32 v64, v184, v64, vcc
	v_lshlrev_b32_e32 v64, 2, v64
	s_nop 1
	v_mov_b32_dpp v64, v65 row_half_mirror row_mask:0xf bank_mask:0xf
	v_cvt_pk_bf16_f32 v71, v66, v67
	v_add3_u32 v66, v165, v81, 48
	v_and_or_b32 v66, v66, s82, v163
	v_lshlrev_b32_e32 v66, 3, v66
	s_waitcnt lgkmcnt(0)
	v_add_f32_e32 v64, v65, v64
	v_xor_b32_e32 v65, 8, v184
	v_cmp_lt_i32_e32 vcc, v65, v187
	v_bitop3_b32 v66, v66, 24, v154 bitop3:0x36
	v_lshlrev_b32_e32 v160, 1, v66
	v_cndmask_b32_e32 v65, v184, v65, vcc
	v_lshlrev_b32_e32 v65, 2, v65
	s_nop 1
	v_mov_b32_dpp v65, v64 row_mirror row_mask:0xf bank_mask:0xf
	v_lshl_add_u64 v[66:67], v[136:137], 0, v[160:161]
	global_store_dwordx2 v[66:67], v[70:71], off
	s_and_saveexec_b64 s[4:5], s[38:39]
	s_cbranch_execz .Lg1r0k2_235
	s_waitcnt lgkmcnt(0)
	v_add_f32_e32 v66, v64, v65
	v_lshl_add_u64 v[64:65], v[72:73], 2, s[24:25]
	global_atomic_add_f32 v[64:65], v66, off
	s_branch .Lg1r0k2_235

; DI unsigned pk2(float lo, float hi) { f32x2 v = {lo, hi}; bfv2 b = __builtin_convertvector(v, bfv2); return __builtin_bit_cast(unsigned, b); }
; DI size_t tidxA(int row, int k) { return ((size_t)(row >> 8) * 32 + (k >> 5)) * 8192 + (size_t)(swz_chunk(row & 255, (k & 31) >> 3) * 8 + (k & 7)); }
; template <int MODE>
; DI void gemm_phase(const Params& p, int layer, unsigned char* lds) {
;     ...
;             const float* xr = layer == 0 ? (row < T_PROMPT ? p.x_prompt + (size_t)row * 1024 : p.x_sample + (size_t)(row - T_PROMPT) * 1024) : p.out + (size_t)row * 1024;
;             const f32x4 xv = *(const f32x4*)(xr + colg);
;             const f32x4 o = xv + cv;
;             *(f32x4*)(p.out + (size_t)row * 1024 + colg) = o;
;             if (layer == 0) {
;               *(u32x2*)(xb + tidxA(row, colg)) = (u32x2){pk2(o.x, o.y), pk2(o.z, o.w)};
;               float sq = o.x * o.x + o.y * o.y + o.z * o.z + o.w * o.w;
;               sq += __shfl_xor(sq, 1); sq += __shfl_xor(sq, 2); sq += __shfl_xor(sq, 4); sq += __shfl_xor(sq, 8);
;               if ((lane & 15) == 0) __hip_atomic_fetch_add(ssq + T_TOK + row, sq, __ATOMIC_RELAXED, __HIP_MEMORY_SCOPE_AGENT);
;             }
.Lg1r0k3_245:
	v_lshl_add_u64 v[74:75], v[134:135], 2, v[74:75]
	v_cndmask_b32_e64 v79, 0, 1, s[36:37]
	v_lshl_add_u64 v[72:73], v[68:69], 0, v[72:73]
	v_cmp_ne_u32_e64 s[40:41], 1, v79
	s_andn2_b64 vcc, exec, s[36:37]
	v_lshlrev_b32_e32 v79, 1, v154
	s_waitcnt vmcnt(15) lgkmcnt(0)
	v_pk_add_f32 v[66:67], v[66:67], v[214:215]
	v_pk_add_f32 v[64:65], v[64:65], v[212:213]
	global_store_dwordx4 v[72:73], v[64:67], off
	s_cbranch_vccnz .Lg1r0k3_249
	v_mul_f32_e32 v72, v65, v65
	v_fmac_f32_e32 v72, v64, v64
	v_cmp_lt_i32_e32 vcc, v185, v187
	v_fmac_f32_e32 v72, v66, v66
	v_fmac_f32_e32 v72, v67, v67
	v_cndmask_b32_e32 v73, v184, v185, vcc
	v_lshlrev_b32_e32 v73, 2, v73
	s_nop 1
	v_mov_b32_dpp v73, v72 quad_perm:[1,0,3,2] row_mask:0xf bank_mask:0xf
	v_cmp_lt_i32_e32 vcc, v188, v187
	v_xor_b32_e32 v74, 4, v184
	s_movk_i32 s2, 0x3cc
	s_waitcnt lgkmcnt(0)
	v_add_f32_e32 v72, v72, v73
	v_cndmask_b32_e32 v73, v184, v188, vcc
	v_lshlrev_b32_e32 v73, 2, v73
	s_nop 1
	v_mov_b32_dpp v73, v72 quad_perm:[2,3,0,1] row_mask:0xf bank_mask:0xf
	v_cmp_lt_i32_e32 vcc, v74, v187
	s_waitcnt lgkmcnt(0)
	v_add_f32_e32 v75, v72, v73
	v_cndmask_b32_e32 v72, v184, v74, vcc
	v_lshlrev_b32_e32 v72, 2, v72
	s_nop 1
	v_mov_b32_dpp v74, v75 row_half_mirror row_mask:0xf bank_mask:0xf
	v_cvt_pk_bf16_f32 v72, v64, v65
	v_xor_b32_e32 v65, 8, v184
	v_cmp_lt_i32_e32 vcc, v65, v187
	v_cvt_pk_bf16_f32 v73, v66, v67
	s_waitcnt lgkmcnt(0)
	v_add_f32_e32 v64, v75, v74
	v_cndmask_b32_e32 v65, v184, v65, vcc
	v_lshlrev_b32_e32 v65, 2, v65
	s_nop 1
	v_mov_b32_dpp v65, v64 row_mirror row_mask:0xf bank_mask:0xf
	v_add_u32_e32 v66, v165, v81
	v_and_or_b32 v66, v66, s2, v163
	v_lshl_or_b32 v160, v66, 4, v79
	v_lshl_add_u64 v[66:67], v[136:137], 0, v[160:161]
	global_store_dwordx2 v[66:67], v[72:73], off
	s_and_saveexec_b64 s[4:5], s[38:39]
	s_cbranch_execz .Lg1r0k3_248
	s_waitcnt lgkmcnt(0)
	v_add_f32_e32 v66, v64, v65
	v_lshl_add_u64 v[64:65], v[70:71], 2, s[24:25]
	global_atomic_add_f32 v[64:65], v66, off

; DI unsigned pk2(float lo, float hi) { f32x2 v = {lo, hi}; bfv2 b = __builtin_convertvector(v, bfv2); return __builtin_bit_cast(unsigned, b); }
; DI size_t tidxA(int row, int k) { return ((size_t)(row >> 8) * 32 + (k >> 5)) * 8192 + (size_t)(swz_chunk(row & 255, (k & 31) >> 3) * 8 + (k & 7)); }
; template <int MODE>
; DI void gemm_phase(const Params& p, int layer, unsigned char* lds) {
;     ...
;             const float* xr = layer == 0 ? (row < T_PROMPT ? p.x_prompt + (size_t)row * 1024 : p.x_sample + (size_t)(row - T_PROMPT) * 1024) : p.out + (size_t)row * 1024;
;             const f32x4 xv = *(const f32x4*)(xr + colg);
;             const f32x4 o = xv + cv;
;             *(f32x4*)(p.out + (size_t)row * 1024 + colg) = o;
;             if (layer == 0) {
;               *(u32x2*)(xb + tidxA(row, colg)) = (u32x2){pk2(o.x, o.y), pk2(o.z, o.w)};
;               float sq = o.x * o.x + o.y * o.y + o.z * o.z + o.w * o.w;
;               sq += __shfl_xor(sq, 1); sq += __shfl_xor(sq, 2); sq += __shfl_xor(sq, 4); sq += __shfl_xor(sq, 8);
;               if ((lane & 15) == 0) __hip_atomic_fetch_add(ssq + T_TOK + row, sq, __ATOMIC_RELAXED, __HIP_MEMORY_SCOPE_AGENT);
;             }
.Lg1r0k3_257:
	v_lshl_add_u64 v[76:77], v[134:135], 2, v[76:77]
	v_lshl_add_u64 v[74:75], v[68:69], 0, v[74:75]
	s_and_b64 vcc, exec, s[40:41]
	s_waitcnt vmcnt(15) lgkmcnt(0)
	v_pk_add_f32 v[66:67], v[66:67], v[218:219]
	v_pk_add_f32 v[64:65], v[64:65], v[216:217]
	global_store_dwordx4 v[74:75], v[64:67], off
	s_cbranch_vccnz .Lg1r0k3_261
	v_mul_f32_e32 v71, v65, v65
	v_fmac_f32_e32 v71, v64, v64
	v_cmp_lt_i32_e32 vcc, v185, v187
	v_fmac_f32_e32 v71, v66, v66
	v_fmac_f32_e32 v71, v67, v67
	v_cndmask_b32_e32 v74, v184, v185, vcc
	v_lshlrev_b32_e32 v74, 2, v74
	s_nop 1
	v_mov_b32_dpp v74, v71 quad_perm:[1,0,3,2] row_mask:0xf bank_mask:0xf
	v_cmp_lt_i32_e32 vcc, v188, v187
	s_waitcnt lgkmcnt(0)
	v_add_f32_e32 v71, v71, v74
	v_cndmask_b32_e32 v74, v184, v188, vcc
	v_lshlrev_b32_e32 v74, 2, v74
	s_nop 1
	v_mov_b32_dpp v75, v71 quad_perm:[2,3,0,1] row_mask:0xf bank_mask:0xf
	v_cvt_pk_bf16_f32 v74, v64, v65
	v_xor_b32_e32 v64, 4, v184
	v_cmp_lt_i32_e32 vcc, v64, v187
	s_waitcnt lgkmcnt(0)
	v_add_f32_e32 v65, v71, v75
	v_cndmask_b32_e32 v64, v184, v64, vcc
	v_lshlrev_b32_e32 v64, 2, v64
	s_nop 1
	v_mov_b32_dpp v64, v65 row_half_mirror row_mask:0xf bank_mask:0xf
	v_cvt_pk_bf16_f32 v75, v66, v67
	v_add3_u32 v66, v165, v81, 16
	v_and_or_b32 v66, v66, s82, v163
	v_lshlrev_b32_e32 v66, 3, v66
	s_waitcnt lgkmcnt(0)
	v_add_f32_e32 v64, v65, v64
	v_xor_b32_e32 v65, 8, v184
	v_cmp_lt_i32_e32 vcc, v65, v187
	v_bitop3_b32 v66, v66, 8, v154 bitop3:0x36
	v_lshlrev_b32_e32 v160, 1, v66
	v_cndmask_b32_e32 v65, v184, v65, vcc
	v_lshlrev_b32_e32 v65, 2, v65
	s_nop 1
	v_mov_b32_dpp v65, v64 row_mirror row_mask:0xf bank_mask:0xf
	v_lshl_add_u64 v[66:67], v[136:137], 0, v[160:161]
	global_store_dwordx2 v[66:67], v[74:75], off
	s_and_saveexec_b64 s[4:5], s[38:39]
	s_cbranch_execz .Lg1r0k3_260
	s_waitcnt lgkmcnt(0)
	v_add_f32_e32 v66, v64, v65
	v_lshl_add_u64 v[64:65], v[72:73], 2, s[24:25]
	global_atomic_add_f32 v[64:65], v66, off

; DI unsigned pk2(float lo, float hi) { f32x2 v = {lo, hi}; bfv2 b = __builtin_convertvector(v, bfv2); return __builtin_bit_cast(unsigned, b); }
; DI size_t tidxA(int row, int k) { return ((size_t)(row >> 8) * 32 + (k >> 5)) * 8192 + (size_t)(swz_chunk(row & 255, (k & 31) >> 3) * 8 + (k & 7)); }
; template <int MODE>
; DI void gemm_phase(const Params& p, int layer, unsigned char* lds) {
;     ...
;             const float* xr = layer == 0 ? (row < T_PROMPT ? p.x_prompt + (size_t)row * 1024 : p.x_sample + (size_t)(row - T_PROMPT) * 1024) : p.out + (size_t)row * 1024;
;             const f32x4 xv = *(const f32x4*)(xr + colg);
;             const f32x4 o = xv + cv;
;             *(f32x4*)(p.out + (size_t)row * 1024 + colg) = o;
;             if (layer == 0) {
;               *(u32x2*)(xb + tidxA(row, colg)) = (u32x2){pk2(o.x, o.y), pk2(o.z, o.w)};
;               float sq = o.x * o.x + o.y * o.y + o.z * o.z + o.w * o.w;
;               sq += __shfl_xor(sq, 1); sq += __shfl_xor(sq, 2); sq += __shfl_xor(sq, 4); sq += __shfl_xor(sq, 8);
;               if ((lane & 15) == 0) __hip_atomic_fetch_add(ssq + T_TOK + row, sq, __ATOMIC_RELAXED, __HIP_MEMORY_SCOPE_AGENT);
;             }
.Lg1r0k3_269:
	v_lshl_add_u64 v[76:77], v[134:135], 2, v[76:77]
	v_lshl_add_u64 v[74:75], v[68:69], 0, v[74:75]
	s_and_b64 vcc, exec, s[40:41]
	s_waitcnt vmcnt(15) lgkmcnt(0)
	v_pk_add_f32 v[66:67], v[66:67], v[222:223]
	v_pk_add_f32 v[64:65], v[64:65], v[220:221]
	global_store_dwordx4 v[74:75], v[64:67], off
	s_cbranch_vccnz .Lg1r0k3_273
	v_mul_f32_e32 v71, v65, v65
	v_fmac_f32_e32 v71, v64, v64
	v_cmp_lt_i32_e32 vcc, v185, v187
	v_fmac_f32_e32 v71, v66, v66
	v_fmac_f32_e32 v71, v67, v67
	v_cndmask_b32_e32 v74, v184, v185, vcc
	v_lshlrev_b32_e32 v74, 2, v74
	s_nop 1
	v_mov_b32_dpp v74, v71 quad_perm:[1,0,3,2] row_mask:0xf bank_mask:0xf
	v_cmp_lt_i32_e32 vcc, v188, v187
	s_waitcnt lgkmcnt(0)
	v_add_f32_e32 v71, v71, v74
	v_cndmask_b32_e32 v74, v184, v188, vcc
	v_lshlrev_b32_e32 v74, 2, v74
	s_nop 1
	v_mov_b32_dpp v75, v71 quad_perm:[2,3,0,1] row_mask:0xf bank_mask:0xf
	v_cvt_pk_bf16_f32 v74, v64, v65
	v_xor_b32_e32 v64, 4, v184
	v_cmp_lt_i32_e32 vcc, v64, v187
	s_waitcnt lgkmcnt(0)
	v_add_f32_e32 v65, v71, v75
	v_cndmask_b32_e32 v64, v184, v64, vcc
	v_lshlrev_b32_e32 v64, 2, v64
	s_nop 1
	v_mov_b32_dpp v64, v65 row_half_mirror row_mask:0xf bank_mask:0xf
	v_cvt_pk_bf16_f32 v75, v66, v67
	v_add3_u32 v66, v165, v81, 32
	v_and_or_b32 v66, v66, s82, v163
	v_lshlrev_b32_e32 v66, 3, v66
	s_waitcnt lgkmcnt(0)
	v_add_f32_e32 v64, v65, v64
	v_xor_b32_e32 v65, 8, v184
	v_cmp_lt_i32_e32 vcc, v65, v187
	v_bitop3_b32 v66, v66, 16, v154 bitop3:0x36
	v_lshlrev_b32_e32 v160, 1, v66
	v_cndmask_b32_e32 v65, v184, v65, vcc
	v_lshlrev_b32_e32 v65, 2, v65
	s_nop 1
	v_mov_b32_dpp v65, v64 row_mirror row_mask:0xf bank_mask:0xf
	v_lshl_add_u64 v[66:67], v[136:137], 0, v[160:161]
	global_store_dwordx2 v[66:67], v[74:75], off
	s_and_saveexec_b64 s[4:5], s[38:39]
	s_cbranch_execz .Lg1r0k3_272
	s_waitcnt lgkmcnt(0)
	v_add_f32_e32 v66, v64, v65
	v_lshl_add_u64 v[64:65], v[72:73], 2, s[24:25]
	global_atomic_add_f32 v[64:65], v66, off

; DI unsigned pk2(float lo, float hi) { f32x2 v = {lo, hi}; bfv2 b = __builtin_convertvector(v, bfv2); return __builtin_bit_cast(unsigned, b); }
; DI size_t tidxA(int row, int k) { return ((size_t)(row >> 8) * 32 + (k >> 5)) * 8192 + (size_t)(swz_chunk(row & 255, (k & 31) >> 3) * 8 + (k & 7)); }
; template <int MODE>
; DI void gemm_phase(const Params& p, int layer, unsigned char* lds) {
;     ...
;             const float* xr = layer == 0 ? (row < T_PROMPT ? p.x_prompt + (size_t)row * 1024 : p.x_sample + (size_t)(row - T_PROMPT) * 1024) : p.out + (size_t)row * 1024;
;             const f32x4 xv = *(const f32x4*)(xr + colg);
;             const f32x4 o = xv + cv;
;             *(f32x4*)(p.out + (size_t)row * 1024 + colg) = o;
;             if (layer == 0) {
;               *(u32x2*)(xb + tidxA(row, colg)) = (u32x2){pk2(o.x, o.y), pk2(o.z, o.w)};
;               float sq = o.x * o.x + o.y * o.y + o.z * o.z + o.w * o.w;
;               sq += __shfl_xor(sq, 1); sq += __shfl_xor(sq, 2); sq += __shfl_xor(sq, 4); sq += __shfl_xor(sq, 8);
;               if ((lane & 15) == 0) __hip_atomic_fetch_add(ssq + T_TOK + row, sq, __ATOMIC_RELAXED, __HIP_MEMORY_SCOPE_AGENT);
;             }
.Lg1r0k3_281:
	v_lshl_add_u64 v[70:71], v[134:135], 2, v[76:77]
	v_lshl_add_u64 v[70:71], v[68:69], 0, v[74:75]
	s_and_b64 vcc, exec, s[40:41]
	s_waitcnt vmcnt(15) lgkmcnt(0)
	v_pk_add_f32 v[66:67], v[66:67], v[230:231]
	v_pk_add_f32 v[64:65], v[64:65], v[228:229]
	global_store_dwordx4 v[70:71], v[64:67], off
	s_cbranch_vccnz .Lg1r0k3_236
	v_mul_f32_e32 v70, v65, v65
	v_fmac_f32_e32 v70, v64, v64
	v_cmp_lt_i32_e32 vcc, v185, v187
	v_fmac_f32_e32 v70, v66, v66
	v_fmac_f32_e32 v70, v67, v67
	v_cndmask_b32_e32 v71, v184, v185, vcc
	v_lshlrev_b32_e32 v71, 2, v71
	s_nop 1
	v_mov_b32_dpp v71, v70 quad_perm:[1,0,3,2] row_mask:0xf bank_mask:0xf
	v_cmp_lt_i32_e32 vcc, v188, v187
	s_waitcnt lgkmcnt(0)
	v_add_f32_e32 v71, v70, v71
	v_cndmask_b32_e32 v70, v184, v188, vcc
	v_lshlrev_b32_e32 v70, 2, v70
	s_nop 1
	v_mov_b32_dpp v74, v71 quad_perm:[2,3,0,1] row_mask:0xf bank_mask:0xf
	v_cvt_pk_bf16_f32 v70, v64, v65
	v_xor_b32_e32 v64, 4, v184
	v_cmp_lt_i32_e32 vcc, v64, v187
	s_waitcnt lgkmcnt(0)
	v_add_f32_e32 v65, v71, v74
	v_cndmask_b32_e32 v64, v184, v64, vcc
	v_lshlrev_b32_e32 v64, 2, v64
	s_nop 1
	v_mov_b32_dpp v64, v65 row_half_mirror row_mask:0xf bank_mask:0xf
	v_cvt_pk_bf16_f32 v71, v66, v67
	v_add3_u32 v66, v165, v81, 48
	v_and_or_b32 v66, v66, s82, v163
	v_lshlrev_b32_e32 v66, 3, v66
	s_waitcnt lgkmcnt(0)
	v_add_f32_e32 v64, v65, v64
	v_xor_b32_e32 v65, 8, v184
	v_cmp_lt_i32_e32 vcc, v65, v187
	v_bitop3_b32 v66, v66, 24, v154 bitop3:0x36
	v_lshlrev_b32_e32 v160, 1, v66
	v_cndmask_b32_e32 v65, v184, v65, vcc
	v_lshlrev_b32_e32 v65, 2, v65
	s_nop 1
	v_mov_b32_dpp v65, v64 row_mirror row_mask:0xf bank_mask:0xf
	v_lshl_add_u64 v[66:67], v[136:137], 0, v[160:161]
	global_store_dwordx2 v[66:67], v[70:71], off
	s_and_saveexec_b64 s[4:5], s[38:39]
	s_cbranch_execz .Lg1r0k3_235
	s_waitcnt lgkmcnt(0)
	v_add_f32_e32 v66, v64, v65
	v_lshl_add_u64 v[64:65], v[72:73], 2, s[24:25]
	global_atomic_add_f32 v[64:65], v66, off
	s_branch .Lg1r0k3_235

; DI unsigned pk2(float lo, float hi) { f32x2 v = {lo, hi}; bfv2 b = __builtin_convertvector(v, bfv2); return __builtin_bit_cast(unsigned, b); }
; DI size_t tidxA(int row, int k) { return ((size_t)(row >> 8) * 32 + (k >> 5)) * 8192 + (size_t)(swz_chunk(row & 255, (k & 31) >> 3) * 8 + (k & 7)); }
; template <int MODE>
; DI void gemm_phase(const Params& p, int layer, unsigned char* lds) {
;     ...
;             const float* xr = layer == 0 ? (row < T_PROMPT ? p.x_prompt + (size_t)row * 1024 : p.x_sample + (size_t)(row - T_PROMPT) * 1024) : p.out + (size_t)row * 1024;
;             const f32x4 xv = *(const f32x4*)(xr + colg);
;             const f32x4 o = xv + cv;
;             *(f32x4*)(p.out + (size_t)row * 1024 + colg) = o;
;             if (layer == 0) {
;               *(u32x2*)(xb + tidxA(row, colg)) = (u32x2){pk2(o.x, o.y), pk2(o.z, o.w)};
;               float sq = o.x * o.x + o.y * o.y + o.z * o.z + o.w * o.w;
;               sq += __shfl_xor(sq, 1); sq += __shfl_xor(sq, 2); sq += __shfl_xor(sq, 4); sq += __shfl_xor(sq, 8);
;               if ((lane & 15) == 0) __hip_atomic_fetch_add(ssq + T_TOK + row, sq, __ATOMIC_RELAXED, __HIP_MEMORY_SCOPE_AGENT);
;             }
.Lg1r1k0_295:
	v_lshl_add_u64 v[8:9], v[134:135], 2, v[8:9]
	v_lshl_add_u64 v[6:7], v[68:69], 0, v[6:7]
	s_and_b64 vcc, exec, s[40:41]
	s_waitcnt vmcnt(15) lgkmcnt(0)
	v_pk_add_f32 v[2:3], v[2:3], v[90:91]
	v_pk_add_f32 v[0:1], v[0:1], v[88:89]
	global_store_dwordx4 v[6:7], v[0:3], off
	s_cbranch_vccnz .Lg1r1k0_299
	v_mul_f32_e32 v6, v1, v1
	v_fmac_f32_e32 v6, v0, v0
	v_cmp_lt_i32_e32 vcc, v185, v187
	v_fmac_f32_e32 v6, v2, v2
	v_fmac_f32_e32 v6, v3, v3
	v_cndmask_b32_e32 v7, v184, v185, vcc
	v_lshlrev_b32_e32 v7, 2, v7
	s_nop 1
	v_mov_b32_dpp v7, v6 quad_perm:[1,0,3,2] row_mask:0xf bank_mask:0xf
	v_cmp_lt_i32_e32 vcc, v188, v187
	s_waitcnt lgkmcnt(0)
	v_add_f32_e32 v8, v6, v7
	v_cndmask_b32_e32 v6, v184, v188, vcc
	v_lshlrev_b32_e32 v6, 2, v6
	s_nop 1
	v_mov_b32_dpp v9, v8 quad_perm:[2,3,0,1] row_mask:0xf bank_mask:0xf
	v_cvt_pk_bf16_f32 v6, v0, v1
	v_xor_b32_e32 v1, 4, v184
	v_cmp_lt_i32_e32 vcc, v1, v187
	v_cvt_pk_bf16_f32 v7, v2, v3
	s_waitcnt lgkmcnt(0)
	v_add_f32_e32 v0, v8, v9
	v_cndmask_b32_e32 v1, v184, v1, vcc
	v_lshlrev_b32_e32 v1, 2, v1
	s_nop 1
	v_mov_b32_dpp v1, v0 row_half_mirror row_mask:0xf bank_mask:0xf
	v_add_u32_e32 v2, 0x100, v10
	v_lshrrev_b32_e32 v3, 2, v4
	v_and_b32_e32 v2, 0x3cc, v2
	v_xor_b32_e32 v3, v3, v153
	s_waitcnt lgkmcnt(0)
	v_add_f32_e32 v0, v0, v1
	v_xor_b32_e32 v1, 8, v184
	v_cmp_lt_i32_e32 vcc, v1, v187
	v_and_or_b32 v2, v3, 3, v2
	v_lshl_or_b32 v160, v2, 4, v79
	v_cndmask_b32_e32 v1, v184, v1, vcc
	v_lshlrev_b32_e32 v1, 2, v1
	s_nop 1
	v_mov_b32_dpp v1, v0 row_mirror row_mask:0xf bank_mask:0xf
	v_lshl_add_u64 v[2:3], v[136:137], 0, v[160:161]
	global_store_dwordx2 v[2:3], v[6:7], off
	s_and_saveexec_b64 s[4:5], s[38:39]
	s_cbranch_execz .Lg1r1k0_298
	s_waitcnt lgkmcnt(0)
	v_add_f32_e32 v2, v0, v1
	v_lshl_add_u64 v[0:1], v[4:5], 2, s[24:25]
	global_atomic_add_f32 v[0:1], v2, off

; DI unsigned pk2(float lo, float hi) { f32x2 v = {lo, hi}; bfv2 b = __builtin_convertvector(v, bfv2); return __builtin_bit_cast(unsigned, b); }
; DI size_t tidxA(int row, int k) { return ((size_t)(row >> 8) * 32 + (k >> 5)) * 8192 + (size_t)(swz_chunk(row & 255, (k & 31) >> 3) * 8 + (k & 7)); }
; template <int MODE>
; DI void gemm_phase(const Params& p, int layer, unsigned char* lds) {
;     ...
;             const float* xr = layer == 0 ? (row < T_PROMPT ? p.x_prompt + (size_t)row * 1024 : p.x_sample + (size_t)(row - T_PROMPT) * 1024) : p.out + (size_t)row * 1024;
;             const f32x4 xv = *(const f32x4*)(xr + colg);
;             const f32x4 o = xv + cv;
;             *(f32x4*)(p.out + (size_t)row * 1024 + colg) = o;
;             if (layer == 0) {
;               *(u32x2*)(xb + tidxA(row, colg)) = (u32x2){pk2(o.x, o.y), pk2(o.z, o.w)};
;               float sq = o.x * o.x + o.y * o.y + o.z * o.z + o.w * o.w;
;               sq += __shfl_xor(sq, 1); sq += __shfl_xor(sq, 2); sq += __shfl_xor(sq, 4); sq += __shfl_xor(sq, 8);
;               if ((lane & 15) == 0) __hip_atomic_fetch_add(ssq + T_TOK + row, sq, __ATOMIC_RELAXED, __HIP_MEMORY_SCOPE_AGENT);
;             }
.Lg1r1k0_307:
	v_lshl_add_u64 v[8:9], v[134:135], 2, v[8:9]
	v_lshl_add_u64 v[6:7], v[68:69], 0, v[6:7]
	s_and_b64 vcc, exec, s[40:41]
	s_waitcnt vmcnt(15) lgkmcnt(0)
	v_pk_add_f32 v[2:3], v[2:3], v[94:95]
	v_pk_add_f32 v[0:1], v[0:1], v[92:93]
	global_store_dwordx4 v[6:7], v[0:3], off
	s_cbranch_vccnz .Lg1r1k0_311
	v_mul_f32_e32 v6, v1, v1
	v_fmac_f32_e32 v6, v0, v0
	v_cmp_lt_i32_e32 vcc, v185, v187
	v_fmac_f32_e32 v6, v2, v2
	v_fmac_f32_e32 v6, v3, v3
	v_cndmask_b32_e32 v7, v184, v185, vcc
	v_lshlrev_b32_e32 v7, 2, v7
	s_nop 1
	v_mov_b32_dpp v7, v6 quad_perm:[1,0,3,2] row_mask:0xf bank_mask:0xf
	v_cmp_lt_i32_e32 vcc, v188, v187
	s_waitcnt lgkmcnt(0)
	v_add_f32_e32 v8, v6, v7
	v_cndmask_b32_e32 v6, v184, v188, vcc
	v_lshlrev_b32_e32 v6, 2, v6
	s_nop 1
	v_mov_b32_dpp v9, v8 quad_perm:[2,3,0,1] row_mask:0xf bank_mask:0xf
	v_cvt_pk_bf16_f32 v6, v0, v1
	v_xor_b32_e32 v1, 4, v184
	v_cmp_lt_i32_e32 vcc, v1, v187
	v_cvt_pk_bf16_f32 v7, v2, v3
	s_waitcnt lgkmcnt(0)
	v_add_f32_e32 v0, v8, v9
	v_cndmask_b32_e32 v1, v184, v1, vcc
	v_lshlrev_b32_e32 v1, 2, v1
	s_nop 1
	v_mov_b32_dpp v1, v0 row_half_mirror row_mask:0xf bank_mask:0xf
	v_add_u32_e32 v2, 0x110, v10
	v_lshrrev_b32_e32 v3, 2, v4
	v_and_b32_e32 v2, 0x3fc, v2
	v_xor_b32_e32 v3, v3, v153
	s_waitcnt lgkmcnt(0)
	v_add_f32_e32 v0, v0, v1
	v_xor_b32_e32 v1, 8, v184
	v_cmp_lt_i32_e32 vcc, v1, v187
	v_and_or_b32 v2, v3, 3, v2
	v_lshl_or_b32 v160, v2, 4, v79
	v_cndmask_b32_e32 v1, v184, v1, vcc
	v_lshlrev_b32_e32 v1, 2, v1
	s_nop 1
	v_mov_b32_dpp v1, v0 row_mirror row_mask:0xf bank_mask:0xf
	v_lshl_add_u64 v[2:3], v[136:137], 0, v[160:161]
	global_store_dwordx2 v[2:3], v[6:7], off
	s_and_saveexec_b64 s[4:5], s[38:39]
	s_cbranch_execz .Lg1r1k0_310
	s_waitcnt lgkmcnt(0)
	v_add_f32_e32 v2, v0, v1
	v_lshl_add_u64 v[0:1], v[4:5], 2, s[24:25]
	global_atomic_add_f32 v[0:1], v2, off

; DI unsigned pk2(float lo, float hi) { f32x2 v = {lo, hi}; bfv2 b = __builtin_convertvector(v, bfv2); return __builtin_bit_cast(unsigned, b); }
; DI size_t tidxA(int row, int k) { return ((size_t)(row >> 8) * 32 + (k >> 5)) * 8192 + (size_t)(swz_chunk(row & 255, (k & 31) >> 3) * 8 + (k & 7)); }
; template <int MODE>
; DI void gemm_phase(const Params& p, int layer, unsigned char* lds) {
;     ...
;             const float* xr = layer == 0 ? (row < T_PROMPT ? p.x_prompt + (size_t)row * 1024 : p.x_sample + (size_t)(row - T_PROMPT) * 1024) : p.out + (size_t)row * 1024;
;             const f32x4 xv = *(const f32x4*)(xr + colg);
;             const f32x4 o = xv + cv;
;             *(f32x4*)(p.out + (size_t)row * 1024 + colg) = o;
;             if (layer == 0) {
;               *(u32x2*)(xb + tidxA(row, colg)) = (u32x2){pk2(o.x, o.y), pk2(o.z, o.w)};
;               float sq = o.x * o.x + o.y * o.y + o.z * o.z + o.w * o.w;
;               sq += __shfl_xor(sq, 1); sq += __shfl_xor(sq, 2); sq += __shfl_xor(sq, 4); sq += __shfl_xor(sq, 8);
;               if ((lane & 15) == 0) __hip_atomic_fetch_add(ssq + T_TOK + row, sq, __ATOMIC_RELAXED, __HIP_MEMORY_SCOPE_AGENT);
;             }
.Lg1r1k0_319:
	v_lshl_add_u64 v[8:9], v[134:135], 2, v[8:9]
	v_lshl_add_u64 v[6:7], v[68:69], 0, v[6:7]
	s_and_b64 vcc, exec, s[40:41]
	s_waitcnt vmcnt(15) lgkmcnt(0)
	v_pk_add_f32 v[2:3], v[2:3], v[98:99]
	v_pk_add_f32 v[0:1], v[0:1], v[96:97]
	global_store_dwordx4 v[6:7], v[0:3], off
	s_cbranch_vccnz .Lg1r1k0_323
	v_mul_f32_e32 v6, v1, v1
	v_fmac_f32_e32 v6, v0, v0
	v_cmp_lt_i32_e32 vcc, v185, v187
	v_fmac_f32_e32 v6, v2, v2
	v_fmac_f32_e32 v6, v3, v3
	v_cndmask_b32_e32 v7, v184, v185, vcc
	v_lshlrev_b32_e32 v7, 2, v7
	s_nop 1
	v_mov_b32_dpp v7, v6 quad_perm:[1,0,3,2] row_mask:0xf bank_mask:0xf
	v_cmp_lt_i32_e32 vcc, v188, v187
	s_waitcnt lgkmcnt(0)
	v_add_f32_e32 v8, v6, v7
	v_cndmask_b32_e32 v6, v184, v188, vcc
	v_lshlrev_b32_e32 v6, 2, v6
	s_nop 1
	v_mov_b32_dpp v9, v8 quad_perm:[2,3,0,1] row_mask:0xf bank_mask:0xf
	v_cvt_pk_bf16_f32 v6, v0, v1
	v_xor_b32_e32 v1, 4, v184
	v_cmp_lt_i32_e32 vcc, v1, v187
	v_cvt_pk_bf16_f32 v7, v2, v3
	s_waitcnt lgkmcnt(0)
	v_add_f32_e32 v0, v8, v9
	v_cndmask_b32_e32 v1, v184, v1, vcc
	v_lshlrev_b32_e32 v1, 2, v1
	s_nop 1
	v_mov_b32_dpp v1, v0 row_half_mirror row_mask:0xf bank_mask:0xf
	v_add_u32_e32 v2, 0x120, v10
	v_lshrrev_b32_e32 v3, 2, v4
	v_and_b32_e32 v2, 0x3fc, v2
	v_xor_b32_e32 v3, v3, v153
	s_waitcnt lgkmcnt(0)
	v_add_f32_e32 v0, v0, v1
	v_xor_b32_e32 v1, 8, v184
	v_cmp_lt_i32_e32 vcc, v1, v187
	v_and_or_b32 v2, v3, 3, v2
	v_lshl_or_b32 v160, v2, 4, v79
	v_cndmask_b32_e32 v1, v184, v1, vcc
	v_lshlrev_b32_e32 v1, 2, v1
	s_nop 1
	v_mov_b32_dpp v1, v0 row_mirror row_mask:0xf bank_mask:0xf
	v_lshl_add_u64 v[2:3], v[136:137], 0, v[160:161]
	global_store_dwordx2 v[2:3], v[6:7], off
	s_and_saveexec_b64 s[4:5], s[38:39]
	s_cbranch_execz .Lg1r1k0_322
	s_waitcnt lgkmcnt(0)
	v_add_f32_e32 v2, v0, v1
	v_lshl_add_u64 v[0:1], v[4:5], 2, s[24:25]
	global_atomic_add_f32 v[0:1], v2, off

; DI unsigned pk2(float lo, float hi) { f32x2 v = {lo, hi}; bfv2 b = __builtin_convertvector(v, bfv2); return __builtin_bit_cast(unsigned, b); }
; DI size_t tidxA(int row, int k) { return ((size_t)(row >> 8) * 32 + (k >> 5)) * 8192 + (size_t)(swz_chunk(row & 255, (k & 31) >> 3) * 8 + (k & 7)); }
; template <int MODE>
; DI void gemm_phase(const Params& p, int layer, unsigned char* lds) {
;     ...
;             const float* xr = layer == 0 ? (row < T_PROMPT ? p.x_prompt + (size_t)row * 1024 : p.x_sample + (size_t)(row - T_PROMPT) * 1024) : p.out + (size_t)row * 1024;
;             const f32x4 xv = *(const f32x4*)(xr + colg);
;             const f32x4 o = xv + cv;
;             *(f32x4*)(p.out + (size_t)row * 1024 + colg) = o;
;             if (layer == 0) {
;               *(u32x2*)(xb + tidxA(row, colg)) = (u32x2){pk2(o.x, o.y), pk2(o.z, o.w)};
;               float sq = o.x * o.x + o.y * o.y + o.z * o.z + o.w * o.w;
;               sq += __shfl_xor(sq, 1); sq += __shfl_xor(sq, 2); sq += __shfl_xor(sq, 4); sq += __shfl_xor(sq, 8);
;               if ((lane & 15) == 0) __hip_atomic_fetch_add(ssq + T_TOK + row, sq, __ATOMIC_RELAXED, __HIP_MEMORY_SCOPE_AGENT);
;             }
.Lg1r1k0_331:
	v_lshl_add_u64 v[8:9], v[134:135], 2, v[8:9]
	v_lshl_add_u64 v[6:7], v[68:69], 0, v[6:7]
	s_and_b64 vcc, exec, s[40:41]
	s_waitcnt vmcnt(15) lgkmcnt(0)
	v_pk_add_f32 v[2:3], v[2:3], v[102:103]
	v_pk_add_f32 v[0:1], v[0:1], v[100:101]
	global_store_dwordx4 v[6:7], v[0:3], off
	s_cbranch_vccnz .Lg1r1k0_286
	v_mul_f32_e32 v6, v1, v1
	v_fmac_f32_e32 v6, v0, v0
	v_cmp_lt_i32_e32 vcc, v185, v187
	v_fmac_f32_e32 v6, v2, v2
	v_fmac_f32_e32 v6, v3, v3
	v_cndmask_b32_e32 v7, v184, v185, vcc
	v_lshlrev_b32_e32 v7, 2, v7
	s_nop 1
	v_mov_b32_dpp v7, v6 quad_perm:[1,0,3,2] row_mask:0xf bank_mask:0xf
	v_cmp_lt_i32_e32 vcc, v188, v187
	s_waitcnt lgkmcnt(0)
	v_add_f32_e32 v8, v6, v7
	v_cndmask_b32_e32 v6, v184, v188, vcc
	v_lshlrev_b32_e32 v6, 2, v6
	s_nop 1
	v_mov_b32_dpp v9, v8 quad_perm:[2,3,0,1] row_mask:0xf bank_mask:0xf
	v_cvt_pk_bf16_f32 v6, v0, v1
	v_xor_b32_e32 v1, 4, v184
	v_cmp_lt_i32_e32 vcc, v1, v187
	v_cvt_pk_bf16_f32 v7, v2, v3
	s_waitcnt lgkmcnt(0)
	v_add_f32_e32 v0, v8, v9
	v_cndmask_b32_e32 v1, v184, v1, vcc
	v_lshlrev_b32_e32 v1, 2, v1
	s_nop 1
	v_mov_b32_dpp v1, v0 row_half_mirror row_mask:0xf bank_mask:0xf
	v_add_u32_e32 v2, 0x130, v10
	v_lshrrev_b32_e32 v3, 2, v4
	v_and_b32_e32 v2, 0x3fc, v2
	v_xor_b32_e32 v3, v3, v153
	s_waitcnt lgkmcnt(0)
	v_add_f32_e32 v0, v0, v1
	v_xor_b32_e32 v1, 8, v184
	v_cmp_lt_i32_e32 vcc, v1, v187
	v_and_or_b32 v2, v3, 3, v2
	v_lshl_or_b32 v160, v2, 4, v79
	v_cndmask_b32_e32 v1, v184, v1, vcc
	v_lshlrev_b32_e32 v1, 2, v1
	s_nop 1
	v_mov_b32_dpp v1, v0 row_mirror row_mask:0xf bank_mask:0xf
	v_lshl_add_u64 v[2:3], v[136:137], 0, v[160:161]
	global_store_dwordx2 v[2:3], v[6:7], off
	s_and_saveexec_b64 s[4:5], s[38:39]
	s_cbranch_execz .Lg1r1k0_285
	s_waitcnt lgkmcnt(0)
	v_add_f32_e32 v2, v0, v1
	v_lshl_add_u64 v[0:1], v[4:5], 2, s[24:25]
	global_atomic_add_f32 v[0:1], v2, off
	s_branch .Lg1r1k0_285

; DI unsigned pk2(float lo, float hi) { f32x2 v = {lo, hi}; bfv2 b = __builtin_convertvector(v, bfv2); return __builtin_bit_cast(unsigned, b); }
; DI size_t tidxA(int row, int k) { return ((size_t)(row >> 8) * 32 + (k >> 5)) * 8192 + (size_t)(swz_chunk(row & 255, (k & 31) >> 3) * 8 + (k & 7)); }
; template <int MODE>
; DI void gemm_phase(const Params& p, int layer, unsigned char* lds) {
;     ...
;             const float* xr = layer == 0 ? (row < T_PROMPT ? p.x_prompt + (size_t)row * 1024 : p.x_sample + (size_t)(row - T_PROMPT) * 1024) : p.out + (size_t)row * 1024;
;             const f32x4 xv = *(const f32x4*)(xr + colg);
;             const f32x4 o = xv + cv;
;             *(f32x4*)(p.out + (size_t)row * 1024 + colg) = o;
;             if (layer == 0) {
;               *(u32x2*)(xb + tidxA(row, colg)) = (u32x2){pk2(o.x, o.y), pk2(o.z, o.w)};
;               float sq = o.x * o.x + o.y * o.y + o.z * o.z + o.w * o.w;
;               sq += __shfl_xor(sq, 1); sq += __shfl_xor(sq, 2); sq += __shfl_xor(sq, 4); sq += __shfl_xor(sq, 8);
;               if ((lane & 15) == 0) __hip_atomic_fetch_add(ssq + T_TOK + row, sq, __ATOMIC_RELAXED, __HIP_MEMORY_SCOPE_AGENT);
;             }
.Lg1r1k1_295:
	v_lshl_add_u64 v[8:9], v[134:135], 2, v[8:9]
	v_lshl_add_u64 v[6:7], v[68:69], 0, v[6:7]
	s_and_b64 vcc, exec, s[40:41]
	s_waitcnt vmcnt(15) lgkmcnt(0)
	v_pk_add_f32 v[2:3], v[2:3], v[106:107]
	v_pk_add_f32 v[0:1], v[0:1], v[104:105]
	global_store_dwordx4 v[6:7], v[0:3], off
	s_cbranch_vccnz .Lg1r1k1_299
	v_mul_f32_e32 v6, v1, v1
	v_fmac_f32_e32 v6, v0, v0
	v_cmp_lt_i32_e32 vcc, v185, v187
	v_fmac_f32_e32 v6, v2, v2
	v_fmac_f32_e32 v6, v3, v3
	v_cndmask_b32_e32 v7, v184, v185, vcc
	v_lshlrev_b32_e32 v7, 2, v7
	s_nop 1
	v_mov_b32_dpp v7, v6 quad_perm:[1,0,3,2] row_mask:0xf bank_mask:0xf
	v_cmp_lt_i32_e32 vcc, v188, v187
	s_waitcnt lgkmcnt(0)
	v_add_f32_e32 v8, v6, v7
	v_cndmask_b32_e32 v6, v184, v188, vcc
	v_lshlrev_b32_e32 v6, 2, v6
	s_nop 1
	v_mov_b32_dpp v9, v8 quad_perm:[2,3,0,1] row_mask:0xf bank_mask:0xf
	v_cvt_pk_bf16_f32 v6, v0, v1
	v_xor_b32_e32 v1, 4, v184
	v_cmp_lt_i32_e32 vcc, v1, v187
	v_cvt_pk_bf16_f32 v7, v2, v3
	s_waitcnt lgkmcnt(0)
	v_add_f32_e32 v0, v8, v9
	v_cndmask_b32_e32 v1, v184, v1, vcc
	v_lshlrev_b32_e32 v1, 2, v1
	s_nop 1
	v_mov_b32_dpp v1, v0 row_half_mirror row_mask:0xf bank_mask:0xf
	v_add_u32_e32 v2, 0x100, v10
	v_lshrrev_b32_e32 v3, 2, v4
	v_and_b32_e32 v2, 0x3cc, v2
	v_xor_b32_e32 v3, v3, v153
	s_waitcnt lgkmcnt(0)
	v_add_f32_e32 v0, v0, v1
	v_xor_b32_e32 v1, 8, v184
	v_cmp_lt_i32_e32 vcc, v1, v187
	v_and_or_b32 v2, v3, 3, v2
	v_lshl_or_b32 v160, v2, 4, v79
	v_cndmask_b32_e32 v1, v184, v1, vcc
	v_lshlrev_b32_e32 v1, 2, v1
	s_nop 1
	v_mov_b32_dpp v1, v0 row_mirror row_mask:0xf bank_mask:0xf
	v_lshl_add_u64 v[2:3], v[136:137], 0, v[160:161]
	global_store_dwordx2 v[2:3], v[6:7], off
	s_and_saveexec_b64 s[4:5], s[38:39]
	s_cbranch_execz .Lg1r1k1_298
	s_waitcnt lgkmcnt(0)
	v_add_f32_e32 v2, v0, v1
	v_lshl_add_u64 v[0:1], v[4:5], 2, s[24:25]
	global_atomic_add_f32 v[0:1], v2, off

; DI unsigned pk2(float lo, float hi) { f32x2 v = {lo, hi}; bfv2 b = __builtin_convertvector(v, bfv2); return __builtin_bit_cast(unsigned, b); }
; DI size_t tidxA(int row, int k) { return ((size_t)(row >> 8) * 32 + (k >> 5)) * 8192 + (size_t)(swz_chunk(row & 255, (k & 31) >> 3) * 8 + (k & 7)); }
; template <int MODE>
; DI void gemm_phase(const Params& p, int layer, unsigned char* lds) {
;     ...
;             const float* xr = layer == 0 ? (row < T_PROMPT ? p.x_prompt + (size_t)row * 1024 : p.x_sample + (size_t)(row - T_PROMPT) * 1024) : p.out + (size_t)row * 1024;
;             const f32x4 xv = *(const f32x4*)(xr + colg);
;             const f32x4 o = xv + cv;
;             *(f32x4*)(p.out + (size_t)row * 1024 + colg) = o;
;             if (layer == 0) {
;               *(u32x2*)(xb + tidxA(row, colg)) = (u32x2){pk2(o.x, o.y), pk2(o.z, o.w)};
;               float sq = o.x * o.x + o.y * o.y + o.z * o.z + o.w * o.w;
;               sq += __shfl_xor(sq, 1); sq += __shfl_xor(sq, 2); sq += __shfl_xor(sq, 4); sq += __shfl_xor(sq, 8);
;               if ((lane & 15) == 0) __hip_atomic_fetch_add(ssq + T_TOK + row, sq, __ATOMIC_RELAXED, __HIP_MEMORY_SCOPE_AGENT);
;             }
.Lg1r1k1_307:
	v_lshl_add_u64 v[8:9], v[134:135], 2, v[8:9]
	v_lshl_add_u64 v[6:7], v[68:69], 0, v[6:7]
	s_and_b64 vcc, exec, s[40:41]
	s_waitcnt vmcnt(15) lgkmcnt(0)
	v_pk_add_f32 v[2:3], v[2:3], v[110:111]
	v_pk_add_f32 v[0:1], v[0:1], v[108:109]
	global_store_dwordx4 v[6:7], v[0:3], off
	s_cbranch_vccnz .Lg1r1k1_311
	v_mul_f32_e32 v6, v1, v1
	v_fmac_f32_e32 v6, v0, v0
	v_cmp_lt_i32_e32 vcc, v185, v187
	v_fmac_f32_e32 v6, v2, v2
	v_fmac_f32_e32 v6, v3, v3
	v_cndmask_b32_e32 v7, v184, v185, vcc
	v_lshlrev_b32_e32 v7, 2, v7
	s_nop 1
	v_mov_b32_dpp v7, v6 quad_perm:[1,0,3,2] row_mask:0xf bank_mask:0xf
	v_cmp_lt_i32_e32 vcc, v188, v187
	s_waitcnt lgkmcnt(0)
	v_add_f32_e32 v8, v6, v7
	v_cndmask_b32_e32 v6, v184, v188, vcc
	v_lshlrev_b32_e32 v6, 2, v6
	s_nop 1
	v_mov_b32_dpp v9, v8 quad_perm:[2,3,0,1] row_mask:0xf bank_mask:0xf
	v_cvt_pk_bf16_f32 v6, v0, v1
	v_xor_b32_e32 v1, 4, v184
	v_cmp_lt_i32_e32 vcc, v1, v187
	v_cvt_pk_bf16_f32 v7, v2, v3
	s_waitcnt lgkmcnt(0)
	v_add_f32_e32 v0, v8, v9
	v_cndmask_b32_e32 v1, v184, v1, vcc
	v_lshlrev_b32_e32 v1, 2, v1
	s_nop 1
	v_mov_b32_dpp v1, v0 row_half_mirror row_mask:0xf bank_mask:0xf
	v_add_u32_e32 v2, 0x110, v10
	v_lshrrev_b32_e32 v3, 2, v4
	v_and_b32_e32 v2, 0x3fc, v2
	v_xor_b32_e32 v3, v3, v153
	s_waitcnt lgkmcnt(0)
	v_add_f32_e32 v0, v0, v1
	v_xor_b32_e32 v1, 8, v184
	v_cmp_lt_i32_e32 vcc, v1, v187
	v_and_or_b32 v2, v3, 3, v2
	v_lshl_or_b32 v160, v2, 4, v79
	v_cndmask_b32_e32 v1, v184, v1, vcc
	v_lshlrev_b32_e32 v1, 2, v1
	s_nop 1
	v_mov_b32_dpp v1, v0 row_mirror row_mask:0xf bank_mask:0xf
	v_lshl_add_u64 v[2:3], v[136:137], 0, v[160:161]
	global_store_dwordx2 v[2:3], v[6:7], off
	s_and_saveexec_b64 s[4:5], s[38:39]
	s_cbranch_execz .Lg1r1k1_310
	s_waitcnt lgkmcnt(0)
	v_add_f32_e32 v2, v0, v1
	v_lshl_add_u64 v[0:1], v[4:5], 2, s[24:25]
	global_atomic_add_f32 v[0:1], v2, off

; DI unsigned pk2(float lo, float hi) { f32x2 v = {lo, hi}; bfv2 b = __builtin_convertvector(v, bfv2); return __builtin_bit_cast(unsigned, b); }
; DI size_t tidxA(int row, int k) { return ((size_t)(row >> 8) * 32 + (k >> 5)) * 8192 + (size_t)(swz_chunk(row & 255, (k & 31) >> 3) * 8 + (k & 7)); }
; template <int MODE>
; DI void gemm_phase(const Params& p, int layer, unsigned char* lds) {
;     ...
;             const float* xr = layer == 0 ? (row < T_PROMPT ? p.x_prompt + (size_t)row * 1024 : p.x_sample + (size_t)(row - T_PROMPT) * 1024) : p.out + (size_t)row * 1024;
;             const f32x4 xv = *(const f32x4*)(xr + colg);
;             const f32x4 o = xv + cv;
;             *(f32x4*)(p.out + (size_t)row * 1024 + colg) = o;
;             if (layer == 0) {
;               *(u32x2*)(xb + tidxA(row, colg)) = (u32x2){pk2(o.x, o.y), pk2(o.z, o.w)};
;               float sq = o.x * o.x + o.y * o.y + o.z * o.z + o.w * o.w;
;               sq += __shfl_xor(sq, 1); sq += __shfl_xor(sq, 2); sq += __shfl_xor(sq, 4); sq += __shfl_xor(sq, 8);
;               if ((lane & 15) == 0) __hip_atomic_fetch_add(ssq + T_TOK + row, sq, __ATOMIC_RELAXED, __HIP_MEMORY_SCOPE_AGENT);
;             }
.Lg1r1k1_319:
	v_lshl_add_u64 v[8:9], v[134:135], 2, v[8:9]
	v_lshl_add_u64 v[6:7], v[68:69], 0, v[6:7]
	s_and_b64 vcc, exec, s[40:41]
	s_waitcnt vmcnt(15) lgkmcnt(0)
	v_pk_add_f32 v[2:3], v[2:3], v[114:115]
	v_pk_add_f32 v[0:1], v[0:1], v[112:113]
	global_store_dwordx4 v[6:7], v[0:3], off
	s_cbranch_vccnz .Lg1r1k1_323
	v_mul_f32_e32 v6, v1, v1
	v_fmac_f32_e32 v6, v0, v0
	v_cmp_lt_i32_e32 vcc, v185, v187
	v_fmac_f32_e32 v6, v2, v2
	v_fmac_f32_e32 v6, v3, v3
	v_cndmask_b32_e32 v7, v184, v185, vcc
	v_lshlrev_b32_e32 v7, 2, v7
	s_nop 1
	v_mov_b32_dpp v7, v6 quad_perm:[1,0,3,2] row_mask:0xf bank_mask:0xf
	v_cmp_lt_i32_e32 vcc, v188, v187
	s_waitcnt lgkmcnt(0)
	v_add_f32_e32 v8, v6, v7
	v_cndmask_b32_e32 v6, v184, v188, vcc
	v_lshlrev_b32_e32 v6, 2, v6
	s_nop 1
	v_mov_b32_dpp v9, v8 quad_perm:[2,3,0,1] row_mask:0xf bank_mask:0xf
	v_cvt_pk_bf16_f32 v6, v0, v1
	v_xor_b32_e32 v1, 4, v184
	v_cmp_lt_i32_e32 vcc, v1, v187
	v_cvt_pk_bf16_f32 v7, v2, v3
	s_waitcnt lgkmcnt(0)
	v_add_f32_e32 v0, v8, v9
	v_cndmask_b32_e32 v1, v184, v1, vcc
	v_lshlrev_b32_e32 v1, 2, v1
	s_nop 1
	v_mov_b32_dpp v1, v0 row_half_mirror row_mask:0xf bank_mask:0xf
	v_add_u32_e32 v2, 0x120, v10
	v_lshrrev_b32_e32 v3, 2, v4
	v_and_b32_e32 v2, 0x3fc, v2
	v_xor_b32_e32 v3, v3, v153
	s_waitcnt lgkmcnt(0)
	v_add_f32_e32 v0, v0, v1
	v_xor_b32_e32 v1, 8, v184
	v_cmp_lt_i32_e32 vcc, v1, v187
	v_and_or_b32 v2, v3, 3, v2
	v_lshl_or_b32 v160, v2, 4, v79
	v_cndmask_b32_e32 v1, v184, v1, vcc
	v_lshlrev_b32_e32 v1, 2, v1
	s_nop 1
	v_mov_b32_dpp v1, v0 row_mirror row_mask:0xf bank_mask:0xf
	v_lshl_add_u64 v[2:3], v[136:137], 0, v[160:161]
	global_store_dwordx2 v[2:3], v[6:7], off
	s_and_saveexec_b64 s[4:5], s[38:39]
	s_cbranch_execz .Lg1r1k1_322
	s_waitcnt lgkmcnt(0)
	v_add_f32_e32 v2, v0, v1
	v_lshl_add_u64 v[0:1], v[4:5], 2, s[24:25]
	global_atomic_add_f32 v[0:1], v2, off

; DI unsigned pk2(float lo, float hi) { f32x2 v = {lo, hi}; bfv2 b = __builtin_convertvector(v, bfv2); return __builtin_bit_cast(unsigned, b); }
; DI size_t tidxA(int row, int k) { return ((size_t)(row >> 8) * 32 + (k >> 5)) * 8192 + (size_t)(swz_chunk(row & 255, (k & 31) >> 3) * 8 + (k & 7)); }
; template <int MODE>
; DI void gemm_phase(const Params& p, int layer, unsigned char* lds) {
;     ...
;             const float* xr = layer == 0 ? (row < T_PROMPT ? p.x_prompt + (size_t)row * 1024 : p.x_sample + (size_t)(row - T_PROMPT) * 1024) : p.out + (size_t)row * 1024;
;             const f32x4 xv = *(const f32x4*)(xr + colg);
;             const f32x4 o = xv + cv;
;             *(f32x4*)(p.out + (size_t)row * 1024 + colg) = o;
;             if (layer == 0) {
;               *(u32x2*)(xb + tidxA(row, colg)) = (u32x2){pk2(o.x, o.y), pk2(o.z, o.w)};
;               float sq = o.x * o.x + o.y * o.y + o.z * o.z + o.w * o.w;
;               sq += __shfl_xor(sq, 1); sq += __shfl_xor(sq, 2); sq += __shfl_xor(sq, 4); sq += __shfl_xor(sq, 8);
;               if ((lane & 15) == 0) __hip_atomic_fetch_add(ssq + T_TOK + row, sq, __ATOMIC_RELAXED, __HIP_MEMORY_SCOPE_AGENT);
;             }
.Lg1r1k1_331:
	v_lshl_add_u64 v[8:9], v[134:135], 2, v[8:9]
	v_lshl_add_u64 v[6:7], v[68:69], 0, v[6:7]
	s_and_b64 vcc, exec, s[40:41]
	s_waitcnt vmcnt(15) lgkmcnt(0)
	v_pk_add_f32 v[2:3], v[2:3], v[118:119]
	v_pk_add_f32 v[0:1], v[0:1], v[116:117]
	global_store_dwordx4 v[6:7], v[0:3], off
	s_cbranch_vccnz .Lg1r1k1_286
	v_mul_f32_e32 v6, v1, v1
	v_fmac_f32_e32 v6, v0, v0
	v_cmp_lt_i32_e32 vcc, v185, v187
	v_fmac_f32_e32 v6, v2, v2
	v_fmac_f32_e32 v6, v3, v3
	v_cndmask_b32_e32 v7, v184, v185, vcc
	v_lshlrev_b32_e32 v7, 2, v7
	s_nop 1
	v_mov_b32_dpp v7, v6 quad_perm:[1,0,3,2] row_mask:0xf bank_mask:0xf
	v_cmp_lt_i32_e32 vcc, v188, v187
	s_waitcnt lgkmcnt(0)
	v_add_f32_e32 v8, v6, v7
	v_cndmask_b32_e32 v6, v184, v188, vcc
	v_lshlrev_b32_e32 v6, 2, v6
	s_nop 1
	v_mov_b32_dpp v9, v8 quad_perm:[2,3,0,1] row_mask:0xf bank_mask:0xf
	v_cvt_pk_bf16_f32 v6, v0, v1
	v_xor_b32_e32 v1, 4, v184
	v_cmp_lt_i32_e32 vcc, v1, v187
	v_cvt_pk_bf16_f32 v7, v2, v3
	s_waitcnt lgkmcnt(0)
	v_add_f32_e32 v0, v8, v9
	v_cndmask_b32_e32 v1, v184, v1, vcc
	v_lshlrev_b32_e32 v1, 2, v1
	s_nop 1
	v_mov_b32_dpp v1, v0 row_half_mirror row_mask:0xf bank_mask:0xf
	v_add_u32_e32 v2, 0x130, v10
	v_lshrrev_b32_e32 v3, 2, v4
	v_and_b32_e32 v2, 0x3fc, v2
	v_xor_b32_e32 v3, v3, v153
	s_waitcnt lgkmcnt(0)
	v_add_f32_e32 v0, v0, v1
	v_xor_b32_e32 v1, 8, v184
	v_cmp_lt_i32_e32 vcc, v1, v187
	v_and_or_b32 v2, v3, 3, v2
	v_lshl_or_b32 v160, v2, 4, v79
	v_cndmask_b32_e32 v1, v184, v1, vcc
	v_lshlrev_b32_e32 v1, 2, v1
	s_nop 1
	v_mov_b32_dpp v1, v0 row_mirror row_mask:0xf bank_mask:0xf
	v_lshl_add_u64 v[2:3], v[136:137], 0, v[160:161]
	global_store_dwordx2 v[2:3], v[6:7], off
	s_and_saveexec_b64 s[4:5], s[38:39]
	s_cbranch_execz .Lg1r1k1_285
	s_waitcnt lgkmcnt(0)
	v_add_f32_e32 v2, v0, v1
	v_lshl_add_u64 v[0:1], v[4:5], 2, s[24:25]
	global_atomic_add_f32 v[0:1], v2, off
	s_branch .Lg1r1k1_285

; DI unsigned pk2(float lo, float hi) { f32x2 v = {lo, hi}; bfv2 b = __builtin_convertvector(v, bfv2); return __builtin_bit_cast(unsigned, b); }
; DI size_t tidxA(int row, int k) { return ((size_t)(row >> 8) * 32 + (k >> 5)) * 8192 + (size_t)(swz_chunk(row & 255, (k & 31) >> 3) * 8 + (k & 7)); }
; template <int MODE>
; DI void gemm_phase(const Params& p, int layer, unsigned char* lds) {
;     ...
;             const float* xr = layer == 0 ? (row < T_PROMPT ? p.x_prompt + (size_t)row * 1024 : p.x_sample + (size_t)(row - T_PROMPT) * 1024) : p.out + (size_t)row * 1024;
;             const f32x4 xv = *(const f32x4*)(xr + colg);
;             const f32x4 o = xv + cv;
;             *(f32x4*)(p.out + (size_t)row * 1024 + colg) = o;
;             if (layer == 0) {
;               *(u32x2*)(xb + tidxA(row, colg)) = (u32x2){pk2(o.x, o.y), pk2(o.z, o.w)};
;               float sq = o.x * o.x + o.y * o.y + o.z * o.z + o.w * o.w;
;               sq += __shfl_xor(sq, 1); sq += __shfl_xor(sq, 2); sq += __shfl_xor(sq, 4); sq += __shfl_xor(sq, 8);
;               if ((lane & 15) == 0) __hip_atomic_fetch_add(ssq + T_TOK + row, sq, __ATOMIC_RELAXED, __HIP_MEMORY_SCOPE_AGENT);
;             }
.Lg1r1k2_295:
	v_lshl_add_u64 v[8:9], v[134:135], 2, v[8:9]
	v_lshl_add_u64 v[6:7], v[68:69], 0, v[6:7]
	s_and_b64 vcc, exec, s[40:41]
	s_waitcnt vmcnt(15) lgkmcnt(0)
	v_pk_add_f32 v[2:3], v[2:3], v[122:123]
	v_pk_add_f32 v[0:1], v[0:1], v[120:121]
	global_store_dwordx4 v[6:7], v[0:3], off
	s_cbranch_vccnz .Lg1r1k2_299
	v_mul_f32_e32 v6, v1, v1
	v_fmac_f32_e32 v6, v0, v0
	v_cmp_lt_i32_e32 vcc, v185, v187
	v_fmac_f32_e32 v6, v2, v2
	v_fmac_f32_e32 v6, v3, v3
	v_cndmask_b32_e32 v7, v184, v185, vcc
	v_lshlrev_b32_e32 v7, 2, v7
	s_nop 1
	v_mov_b32_dpp v7, v6 quad_perm:[1,0,3,2] row_mask:0xf bank_mask:0xf
	v_cmp_lt_i32_e32 vcc, v188, v187
	s_waitcnt lgkmcnt(0)
	v_add_f32_e32 v8, v6, v7
	v_cndmask_b32_e32 v6, v184, v188, vcc
	v_lshlrev_b32_e32 v6, 2, v6
	s_nop 1
	v_mov_b32_dpp v9, v8 quad_perm:[2,3,0,1] row_mask:0xf bank_mask:0xf
	v_cvt_pk_bf16_f32 v6, v0, v1
	v_xor_b32_e32 v1, 4, v184
	v_cmp_lt_i32_e32 vcc, v1, v187
	v_cvt_pk_bf16_f32 v7, v2, v3
	s_waitcnt lgkmcnt(0)
	v_add_f32_e32 v0, v8, v9
	v_cndmask_b32_e32 v1, v184, v1, vcc
	v_lshlrev_b32_e32 v1, 2, v1
	s_nop 1
	v_mov_b32_dpp v1, v0 row_half_mirror row_mask:0xf bank_mask:0xf
	v_add_u32_e32 v2, 0x100, v10
	v_lshrrev_b32_e32 v3, 2, v4
	v_and_b32_e32 v2, 0x3cc, v2
	v_xor_b32_e32 v3, v3, v153
	s_waitcnt lgkmcnt(0)
	v_add_f32_e32 v0, v0, v1
	v_xor_b32_e32 v1, 8, v184
	v_cmp_lt_i32_e32 vcc, v1, v187
	v_and_or_b32 v2, v3, 3, v2
	v_lshl_or_b32 v160, v2, 4, v79
	v_cndmask_b32_e32 v1, v184, v1, vcc
	v_lshlrev_b32_e32 v1, 2, v1
	s_nop 1
	v_mov_b32_dpp v1, v0 row_mirror row_mask:0xf bank_mask:0xf
	v_lshl_add_u64 v[2:3], v[136:137], 0, v[160:161]
	global_store_dwordx2 v[2:3], v[6:7], off
	s_and_saveexec_b64 s[4:5], s[38:39]
	s_cbranch_execz .Lg1r1k2_298
	s_waitcnt lgkmcnt(0)
	v_add_f32_e32 v2, v0, v1
	v_lshl_add_u64 v[0:1], v[4:5], 2, s[24:25]
	global_atomic_add_f32 v[0:1], v2, off

; DI unsigned pk2(float lo, float hi) { f32x2 v = {lo, hi}; bfv2 b = __builtin_convertvector(v, bfv2); return __builtin_bit_cast(unsigned, b); }
; DI size_t tidxA(int row, int k) { return ((size_t)(row >> 8) * 32 + (k >> 5)) * 8192 + (size_t)(swz_chunk(row & 255, (k & 31) >> 3) * 8 + (k & 7)); }
; template <int MODE>
; DI void gemm_phase(const Params& p, int layer, unsigned char* lds) {
;     ...
;             const float* xr = layer == 0 ? (row < T_PROMPT ? p.x_prompt + (size_t)row * 1024 : p.x_sample + (size_t)(row - T_PROMPT) * 1024) : p.out + (size_t)row * 1024;
;             const f32x4 xv = *(const f32x4*)(xr + colg);
;             const f32x4 o = xv + cv;
;             *(f32x4*)(p.out + (size_t)row * 1024 + colg) = o;
;             if (layer == 0) {
;               *(u32x2*)(xb + tidxA(row, colg)) = (u32x2){pk2(o.x, o.y), pk2(o.z, o.w)};
;               float sq = o.x * o.x + o.y * o.y + o.z * o.z + o.w * o.w;
;               sq += __shfl_xor(sq, 1); sq += __shfl_xor(sq, 2); sq += __shfl_xor(sq, 4); sq += __shfl_xor(sq, 8);
;               if ((lane & 15) == 0) __hip_atomic_fetch_add(ssq + T_TOK + row, sq, __ATOMIC_RELAXED, __HIP_MEMORY_SCOPE_AGENT);
;             }
.Lg1r1k2_307:
	v_lshl_add_u64 v[8:9], v[134:135], 2, v[8:9]
	v_lshl_add_u64 v[6:7], v[68:69], 0, v[6:7]
	s_and_b64 vcc, exec, s[40:41]
	s_waitcnt vmcnt(15) lgkmcnt(0)
	v_pk_add_f32 v[2:3], v[2:3], v[126:127]
	v_pk_add_f32 v[0:1], v[0:1], v[124:125]
	global_store_dwordx4 v[6:7], v[0:3], off
	s_cbranch_vccnz .Lg1r1k2_311
	v_mul_f32_e32 v6, v1, v1
	v_fmac_f32_e32 v6, v0, v0
	v_cmp_lt_i32_e32 vcc, v185, v187
	v_fmac_f32_e32 v6, v2, v2
	v_fmac_f32_e32 v6, v3, v3
	v_cndmask_b32_e32 v7, v184, v185, vcc
	v_lshlrev_b32_e32 v7, 2, v7
	s_nop 1
	v_mov_b32_dpp v7, v6 quad_perm:[1,0,3,2] row_mask:0xf bank_mask:0xf
	v_cmp_lt_i32_e32 vcc, v188, v187
	s_waitcnt lgkmcnt(0)
	v_add_f32_e32 v8, v6, v7
	v_cndmask_b32_e32 v6, v184, v188, vcc
	v_lshlrev_b32_e32 v6, 2, v6
	s_nop 1
	v_mov_b32_dpp v9, v8 quad_perm:[2,3,0,1] row_mask:0xf bank_mask:0xf
	v_cvt_pk_bf16_f32 v6, v0, v1
	v_xor_b32_e32 v1, 4, v184
	v_cmp_lt_i32_e32 vcc, v1, v187
	v_cvt_pk_bf16_f32 v7, v2, v3
	s_waitcnt lgkmcnt(0)
	v_add_f32_e32 v0, v8, v9
	v_cndmask_b32_e32 v1, v184, v1, vcc
	v_lshlrev_b32_e32 v1, 2, v1
	s_nop 1
	v_mov_b32_dpp v1, v0 row_half_mirror row_mask:0xf bank_mask:0xf
	v_add_u32_e32 v2, 0x110, v10
	v_lshrrev_b32_e32 v3, 2, v4
	v_and_b32_e32 v2, 0x3fc, v2
	v_xor_b32_e32 v3, v3, v153
	s_waitcnt lgkmcnt(0)
	v_add_f32_e32 v0, v0, v1
	v_xor_b32_e32 v1, 8, v184
	v_cmp_lt_i32_e32 vcc, v1, v187
	v_and_or_b32 v2, v3, 3, v2
	v_lshl_or_b32 v160, v2, 4, v79
	v_cndmask_b32_e32 v1, v184, v1, vcc
	v_lshlrev_b32_e32 v1, 2, v1
	s_nop 1
	v_mov_b32_dpp v1, v0 row_mirror row_mask:0xf bank_mask:0xf
	v_lshl_add_u64 v[2:3], v[136:137], 0, v[160:161]
	global_store_dwordx2 v[2:3], v[6:7], off
	s_and_saveexec_b64 s[4:5], s[38:39]
	s_cbranch_execz .Lg1r1k2_310
	s_waitcnt lgkmcnt(0)
	v_add_f32_e32 v2, v0, v1
	v_lshl_add_u64 v[0:1], v[4:5], 2, s[24:25]
	global_atomic_add_f32 v[0:1], v2, off

; DI unsigned pk2(float lo, float hi) { f32x2 v = {lo, hi}; bfv2 b = __builtin_convertvector(v, bfv2); return __builtin_bit_cast(unsigned, b); }
; DI size_t tidxA(int row, int k) { return ((size_t)(row >> 8) * 32 + (k >> 5)) * 8192 + (size_t)(swz_chunk(row & 255, (k & 31) >> 3) * 8 + (k & 7)); }
; template <int MODE>
; DI void gemm_phase(const Params& p, int layer, unsigned char* lds) {
;     ...
;             const float* xr = layer == 0 ? (row < T_PROMPT ? p.x_prompt + (size_t)row * 1024 : p.x_sample + (size_t)(row - T_PROMPT) * 1024) : p.out + (size_t)row * 1024;
;             const f32x4 xv = *(const f32x4*)(xr + colg);
;             const f32x4 o = xv + cv;
;             *(f32x4*)(p.out + (size_t)row * 1024 + colg) = o;
;             if (layer == 0) {
;               *(u32x2*)(xb + tidxA(row, colg)) = (u32x2){pk2(o.x, o.y), pk2(o.z, o.w)};
;               float sq = o.x * o.x + o.y * o.y + o.z * o.z + o.w * o.w;
;               sq += __shfl_xor(sq, 1); sq += __shfl_xor(sq, 2); sq += __shfl_xor(sq, 4); sq += __shfl_xor(sq, 8);
;               if ((lane & 15) == 0) __hip_atomic_fetch_add(ssq + T_TOK + row, sq, __ATOMIC_RELAXED, __HIP_MEMORY_SCOPE_AGENT);
;             }
.Lg1r1k2_319:
	v_lshl_add_u64 v[8:9], v[134:135], 2, v[8:9]
	v_lshl_add_u64 v[6:7], v[68:69], 0, v[6:7]
	s_and_b64 vcc, exec, s[40:41]
	s_waitcnt vmcnt(15) lgkmcnt(0)
	v_pk_add_f32 v[2:3], v[2:3], v[206:207]
	v_pk_add_f32 v[0:1], v[0:1], v[204:205]
	global_store_dwordx4 v[6:7], v[0:3], off
	s_cbranch_vccnz .Lg1r1k2_323
	v_mul_f32_e32 v6, v1, v1
	v_fmac_f32_e32 v6, v0, v0
	v_cmp_lt_i32_e32 vcc, v185, v187
	v_fmac_f32_e32 v6, v2, v2
	v_fmac_f32_e32 v6, v3, v3
	v_cndmask_b32_e32 v7, v184, v185, vcc
	v_lshlrev_b32_e32 v7, 2, v7
	s_nop 1
	v_mov_b32_dpp v7, v6 quad_perm:[1,0,3,2] row_mask:0xf bank_mask:0xf
	v_cmp_lt_i32_e32 vcc, v188, v187
	s_waitcnt lgkmcnt(0)
	v_add_f32_e32 v8, v6, v7
	v_cndmask_b32_e32 v6, v184, v188, vcc
	v_lshlrev_b32_e32 v6, 2, v6
	s_nop 1
	v_mov_b32_dpp v9, v8 quad_perm:[2,3,0,1] row_mask:0xf bank_mask:0xf
	v_cvt_pk_bf16_f32 v6, v0, v1
	v_xor_b32_e32 v1, 4, v184
	v_cmp_lt_i32_e32 vcc, v1, v187
	v_cvt_pk_bf16_f32 v7, v2, v3
	s_waitcnt lgkmcnt(0)
	v_add_f32_e32 v0, v8, v9
	v_cndmask_b32_e32 v1, v184, v1, vcc
	v_lshlrev_b32_e32 v1, 2, v1
	s_nop 1
	v_mov_b32_dpp v1, v0 row_half_mirror row_mask:0xf bank_mask:0xf
	v_add_u32_e32 v2, 0x120, v10
	v_lshrrev_b32_e32 v3, 2, v4
	v_and_b32_e32 v2, 0x3fc, v2
	v_xor_b32_e32 v3, v3, v153
	s_waitcnt lgkmcnt(0)
	v_add_f32_e32 v0, v0, v1
	v_xor_b32_e32 v1, 8, v184
	v_cmp_lt_i32_e32 vcc, v1, v187
	v_and_or_b32 v2, v3, 3, v2
	v_lshl_or_b32 v160, v2, 4, v79
	v_cndmask_b32_e32 v1, v184, v1, vcc
	v_lshlrev_b32_e32 v1, 2, v1
	s_nop 1
	v_mov_b32_dpp v1, v0 row_mirror row_mask:0xf bank_mask:0xf
	v_lshl_add_u64 v[2:3], v[136:137], 0, v[160:161]
	global_store_dwordx2 v[2:3], v[6:7], off
	s_and_saveexec_b64 s[4:5], s[38:39]
	s_cbranch_execz .Lg1r1k2_322
	s_waitcnt lgkmcnt(0)
	v_add_f32_e32 v2, v0, v1
	v_lshl_add_u64 v[0:1], v[4:5], 2, s[24:25]
	global_atomic_add_f32 v[0:1], v2, off

; DI unsigned pk2(float lo, float hi) { f32x2 v = {lo, hi}; bfv2 b = __builtin_convertvector(v, bfv2); return __builtin_bit_cast(unsigned, b); }
; DI size_t tidxA(int row, int k) { return ((size_t)(row >> 8) * 32 + (k >> 5)) * 8192 + (size_t)(swz_chunk(row & 255, (k & 31) >> 3) * 8 + (k & 7)); }
; template <int MODE>
; DI void gemm_phase(const Params& p, int layer, unsigned char* lds) {
;     ...
;             const float* xr = layer == 0 ? (row < T_PROMPT ? p.x_prompt + (size_t)row * 1024 : p.x_sample + (size_t)(row - T_PROMPT) * 1024) : p.out + (size_t)row * 1024;
;             const f32x4 xv = *(const f32x4*)(xr + colg);
;             const f32x4 o = xv + cv;
;             *(f32x4*)(p.out + (size_t)row * 1024 + colg) = o;
;             if (layer == 0) {
;               *(u32x2*)(xb + tidxA(row, colg)) = (u32x2){pk2(o.x, o.y), pk2(o.z, o.w)};
;               float sq = o.x * o.x + o.y * o.y + o.z * o.z + o.w * o.w;
;               sq += __shfl_xor(sq, 1); sq += __shfl_xor(sq, 2); sq += __shfl_xor(sq, 4); sq += __shfl_xor(sq, 8);
;               if ((lane & 15) == 0) __hip_atomic_fetch_add(ssq + T_TOK + row, sq, __ATOMIC_RELAXED, __HIP_MEMORY_SCOPE_AGENT);
;             }
.Lg1r1k2_331:
	v_lshl_add_u64 v[8:9], v[134:135], 2, v[8:9]
	v_lshl_add_u64 v[6:7], v[68:69], 0, v[6:7]
	s_and_b64 vcc, exec, s[40:41]
	s_waitcnt vmcnt(15) lgkmcnt(0)
	v_pk_add_f32 v[2:3], v[2:3], v[210:211]
	v_pk_add_f32 v[0:1], v[0:1], v[208:209]
	global_store_dwordx4 v[6:7], v[0:3], off
	s_cbranch_vccnz .Lg1r1k2_286
	v_mul_f32_e32 v6, v1, v1
	v_fmac_f32_e32 v6, v0, v0
	v_cmp_lt_i32_e32 vcc, v185, v187
	v_fmac_f32_e32 v6, v2, v2
	v_fmac_f32_e32 v6, v3, v3
	v_cndmask_b32_e32 v7, v184, v185, vcc
	v_lshlrev_b32_e32 v7, 2, v7
	s_nop 1
	v_mov_b32_dpp v7, v6 quad_perm:[1,0,3,2] row_mask:0xf bank_mask:0xf
	v_cmp_lt_i32_e32 vcc, v188, v187
	s_waitcnt lgkmcnt(0)
	v_add_f32_e32 v8, v6, v7
	v_cndmask_b32_e32 v6, v184, v188, vcc
	v_lshlrev_b32_e32 v6, 2, v6
	s_nop 1
	v_mov_b32_dpp v9, v8 quad_perm:[2,3,0,1] row_mask:0xf bank_mask:0xf
	v_cvt_pk_bf16_f32 v6, v0, v1
	v_xor_b32_e32 v1, 4, v184
	v_cmp_lt_i32_e32 vcc, v1, v187
	v_cvt_pk_bf16_f32 v7, v2, v3
	s_waitcnt lgkmcnt(0)
	v_add_f32_e32 v0, v8, v9
	v_cndmask_b32_e32 v1, v184, v1, vcc
	v_lshlrev_b32_e32 v1, 2, v1
	s_nop 1
	v_mov_b32_dpp v1, v0 row_half_mirror row_mask:0xf bank_mask:0xf
	v_add_u32_e32 v2, 0x130, v10
	v_lshrrev_b32_e32 v3, 2, v4
	v_and_b32_e32 v2, 0x3fc, v2
	v_xor_b32_e32 v3, v3, v153
	s_waitcnt lgkmcnt(0)
	v_add_f32_e32 v0, v0, v1
	v_xor_b32_e32 v1, 8, v184
	v_cmp_lt_i32_e32 vcc, v1, v187
	v_and_or_b32 v2, v3, 3, v2
	v_lshl_or_b32 v160, v2, 4, v79
	v_cndmask_b32_e32 v1, v184, v1, vcc
	v_lshlrev_b32_e32 v1, 2, v1
	s_nop 1
	v_mov_b32_dpp v1, v0 row_mirror row_mask:0xf bank_mask:0xf
	v_lshl_add_u64 v[2:3], v[136:137], 0, v[160:161]
	global_store_dwordx2 v[2:3], v[6:7], off
	s_and_saveexec_b64 s[4:5], s[38:39]
	s_cbranch_execz .Lg1r1k2_285
	s_waitcnt lgkmcnt(0)
	v_add_f32_e32 v2, v0, v1
	v_lshl_add_u64 v[0:1], v[4:5], 2, s[24:25]
	global_atomic_add_f32 v[0:1], v2, off
	s_branch .Lg1r1k2_285

; DI unsigned pk2(float lo, float hi) { f32x2 v = {lo, hi}; bfv2 b = __builtin_convertvector(v, bfv2); return __builtin_bit_cast(unsigned, b); }
; DI size_t tidxA(int row, int k) { return ((size_t)(row >> 8) * 32 + (k >> 5)) * 8192 + (size_t)(swz_chunk(row & 255, (k & 31) >> 3) * 8 + (k & 7)); }
; template <int MODE>
; DI void gemm_phase(const Params& p, int layer, unsigned char* lds) {
;     ...
;             const float* xr = layer == 0 ? (row < T_PROMPT ? p.x_prompt + (size_t)row * 1024 : p.x_sample + (size_t)(row - T_PROMPT) * 1024) : p.out + (size_t)row * 1024;
;             const f32x4 xv = *(const f32x4*)(xr + colg);
;             const f32x4 o = xv + cv;
;             *(f32x4*)(p.out + (size_t)row * 1024 + colg) = o;
;             if (layer == 0) {
;               *(u32x2*)(xb + tidxA(row, colg)) = (u32x2){pk2(o.x, o.y), pk2(o.z, o.w)};
;               float sq = o.x * o.x + o.y * o.y + o.z * o.z + o.w * o.w;
;               sq += __shfl_xor(sq, 1); sq += __shfl_xor(sq, 2); sq += __shfl_xor(sq, 4); sq += __shfl_xor(sq, 8);
;               if ((lane & 15) == 0) __hip_atomic_fetch_add(ssq + T_TOK + row, sq, __ATOMIC_RELAXED, __HIP_MEMORY_SCOPE_AGENT);
;             }
.Lg1r1k3_295:
	v_lshl_add_u64 v[8:9], v[134:135], 2, v[8:9]
	v_lshl_add_u64 v[6:7], v[68:69], 0, v[6:7]
	s_and_b64 vcc, exec, s[40:41]
	s_waitcnt vmcnt(15) lgkmcnt(0)
	v_pk_add_f32 v[2:3], v[2:3], v[214:215]
	v_pk_add_f32 v[0:1], v[0:1], v[212:213]
	global_store_dwordx4 v[6:7], v[0:3], off
	s_cbranch_vccnz .Lg1r1k3_299
	v_mul_f32_e32 v6, v1, v1
	v_fmac_f32_e32 v6, v0, v0
	v_cmp_lt_i32_e32 vcc, v185, v187
	v_fmac_f32_e32 v6, v2, v2
	v_fmac_f32_e32 v6, v3, v3
	v_cndmask_b32_e32 v7, v184, v185, vcc
	v_lshlrev_b32_e32 v7, 2, v7
	s_nop 1
	v_mov_b32_dpp v7, v6 quad_perm:[1,0,3,2] row_mask:0xf bank_mask:0xf
	v_cmp_lt_i32_e32 vcc, v188, v187
	s_waitcnt lgkmcnt(0)
	v_add_f32_e32 v8, v6, v7
	v_cndmask_b32_e32 v6, v184, v188, vcc
	v_lshlrev_b32_e32 v6, 2, v6
	s_nop 1
	v_mov_b32_dpp v9, v8 quad_perm:[2,3,0,1] row_mask:0xf bank_mask:0xf
	v_cvt_pk_bf16_f32 v6, v0, v1
	v_xor_b32_e32 v1, 4, v184
	v_cmp_lt_i32_e32 vcc, v1, v187
	v_cvt_pk_bf16_f32 v7, v2, v3
	s_waitcnt lgkmcnt(0)
	v_add_f32_e32 v0, v8, v9
	v_cndmask_b32_e32 v1, v184, v1, vcc
	v_lshlrev_b32_e32 v1, 2, v1
	s_nop 1
	v_mov_b32_dpp v1, v0 row_half_mirror row_mask:0xf bank_mask:0xf
	v_add_u32_e32 v2, 0x100, v10
	v_lshrrev_b32_e32 v3, 2, v4
	v_and_b32_e32 v2, 0x3cc, v2
	v_xor_b32_e32 v3, v3, v153
	s_waitcnt lgkmcnt(0)
	v_add_f32_e32 v0, v0, v1
	v_xor_b32_e32 v1, 8, v184
	v_cmp_lt_i32_e32 vcc, v1, v187
	v_and_or_b32 v2, v3, 3, v2
	v_lshl_or_b32 v160, v2, 4, v79
	v_cndmask_b32_e32 v1, v184, v1, vcc
	v_lshlrev_b32_e32 v1, 2, v1
	s_nop 1
	v_mov_b32_dpp v1, v0 row_mirror row_mask:0xf bank_mask:0xf
	v_lshl_add_u64 v[2:3], v[136:137], 0, v[160:161]
	global_store_dwordx2 v[2:3], v[6:7], off
	s_and_saveexec_b64 s[4:5], s[38:39]
	s_cbranch_execz .Lg1r1k3_298
	s_waitcnt lgkmcnt(0)
	v_add_f32_e32 v2, v0, v1
	v_lshl_add_u64 v[0:1], v[4:5], 2, s[24:25]
	global_atomic_add_f32 v[0:1], v2, off

; DI unsigned pk2(float lo, float hi) { f32x2 v = {lo, hi}; bfv2 b = __builtin_convertvector(v, bfv2); return __builtin_bit_cast(unsigned, b); }
; DI size_t tidxA(int row, int k) { return ((size_t)(row >> 8) * 32 + (k >> 5)) * 8192 + (size_t)(swz_chunk(row & 255, (k & 31) >> 3) * 8 + (k & 7)); }
; template <int MODE>
; DI void gemm_phase(const Params& p, int layer, unsigned char* lds) {
;     ...
;             const float* xr = layer == 0 ? (row < T_PROMPT ? p.x_prompt + (size_t)row * 1024 : p.x_sample + (size_t)(row - T_PROMPT) * 1024) : p.out + (size_t)row * 1024;
;             const f32x4 xv = *(const f32x4*)(xr + colg);
;             const f32x4 o = xv + cv;
;             *(f32x4*)(p.out + (size_t)row * 1024 + colg) = o;
;             if (layer == 0) {
;               *(u32x2*)(xb + tidxA(row, colg)) = (u32x2){pk2(o.x, o.y), pk2(o.z, o.w)};
;               float sq = o.x * o.x + o.y * o.y + o.z * o.z + o.w * o.w;
;               sq += __shfl_xor(sq, 1); sq += __shfl_xor(sq, 2); sq += __shfl_xor(sq, 4); sq += __shfl_xor(sq, 8);
;               if ((lane & 15) == 0) __hip_atomic_fetch_add(ssq + T_TOK + row, sq, __ATOMIC_RELAXED, __HIP_MEMORY_SCOPE_AGENT);
;             }
.Lg1r1k3_307:
	v_lshl_add_u64 v[8:9], v[134:135], 2, v[8:9]
	v_lshl_add_u64 v[6:7], v[68:69], 0, v[6:7]
	s_and_b64 vcc, exec, s[40:41]
	s_waitcnt vmcnt(15) lgkmcnt(0)
	v_pk_add_f32 v[2:3], v[2:3], v[218:219]
	v_pk_add_f32 v[0:1], v[0:1], v[216:217]
	global_store_dwordx4 v[6:7], v[0:3], off
	s_cbranch_vccnz .Lg1r1k3_311
	v_mul_f32_e32 v6, v1, v1
	v_fmac_f32_e32 v6, v0, v0
	v_cmp_lt_i32_e32 vcc, v185, v187
	v_fmac_f32_e32 v6, v2, v2
	v_fmac_f32_e32 v6, v3, v3
	v_cndmask_b32_e32 v7, v184, v185, vcc
	v_lshlrev_b32_e32 v7, 2, v7
	s_nop 1
	v_mov_b32_dpp v7, v6 quad_perm:[1,0,3,2] row_mask:0xf bank_mask:0xf
	v_cmp_lt_i32_e32 vcc, v188, v187
	s_waitcnt lgkmcnt(0)
	v_add_f32_e32 v8, v6, v7
	v_cndmask_b32_e32 v6, v184, v188, vcc
	v_lshlrev_b32_e32 v6, 2, v6
	s_nop 1
	v_mov_b32_dpp v9, v8 quad_perm:[2,3,0,1] row_mask:0xf bank_mask:0xf
	v_cvt_pk_bf16_f32 v6, v0, v1
	v_xor_b32_e32 v1, 4, v184
	v_cmp_lt_i32_e32 vcc, v1, v187
	v_cvt_pk_bf16_f32 v7, v2, v3
	s_waitcnt lgkmcnt(0)
	v_add_f32_e32 v0, v8, v9
	v_cndmask_b32_e32 v1, v184, v1, vcc
	v_lshlrev_b32_e32 v1, 2, v1
	s_nop 1
	v_mov_b32_dpp v1, v0 row_half_mirror row_mask:0xf bank_mask:0xf
	v_add_u32_e32 v2, 0x110, v10
	v_lshrrev_b32_e32 v3, 2, v4
	v_and_b32_e32 v2, 0x3fc, v2
	v_xor_b32_e32 v3, v3, v153
	s_waitcnt lgkmcnt(0)
	v_add_f32_e32 v0, v0, v1
	v_xor_b32_e32 v1, 8, v184
	v_cmp_lt_i32_e32 vcc, v1, v187
	v_and_or_b32 v2, v3, 3, v2
	v_lshl_or_b32 v160, v2, 4, v79
	v_cndmask_b32_e32 v1, v184, v1, vcc
	v_lshlrev_b32_e32 v1, 2, v1
	s_nop 1
	v_mov_b32_dpp v1, v0 row_mirror row_mask:0xf bank_mask:0xf
	v_lshl_add_u64 v[2:3], v[136:137], 0, v[160:161]
	global_store_dwordx2 v[2:3], v[6:7], off
	s_and_saveexec_b64 s[4:5], s[38:39]
	s_cbranch_execz .Lg1r1k3_310
	s_waitcnt lgkmcnt(0)
	v_add_f32_e32 v2, v0, v1
	v_lshl_add_u64 v[0:1], v[4:5], 2, s[24:25]
	global_atomic_add_f32 v[0:1], v2, off

; DI unsigned pk2(float lo, float hi) { f32x2 v = {lo, hi}; bfv2 b = __builtin_convertvector(v, bfv2); return __builtin_bit_cast(unsigned, b); }
; DI size_t tidxA(int row, int k) { return ((size_t)(row >> 8) * 32 + (k >> 5)) * 8192 + (size_t)(swz_chunk(row & 255, (k & 31) >> 3) * 8 + (k & 7)); }
; template <int MODE>
; DI void gemm_phase(const Params& p, int layer, unsigned char* lds) {
;     ...
;             const float* xr = layer == 0 ? (row < T_PROMPT ? p.x_prompt + (size_t)row * 1024 : p.x_sample + (size_t)(row - T_PROMPT) * 1024) : p.out + (size_t)row * 1024;
;             const f32x4 xv = *(const f32x4*)(xr + colg);
;             const f32x4 o = xv + cv;
;             *(f32x4*)(p.out + (size_t)row * 1024 + colg) = o;
;             if (layer == 0) {
;               *(u32x2*)(xb + tidxA(row, colg)) = (u32x2){pk2(o.x, o.y), pk2(o.z, o.w)};
;               float sq = o.x * o.x + o.y * o.y + o.z * o.z + o.w * o.w;
;               sq += __shfl_xor(sq, 1); sq += __shfl_xor(sq, 2); sq += __shfl_xor(sq, 4); sq += __shfl_xor(sq, 8);
;               if ((lane & 15) == 0) __hip_atomic_fetch_add(ssq + T_TOK + row, sq, __ATOMIC_RELAXED, __HIP_MEMORY_SCOPE_AGENT);
;             }
.Lg1r1k3_319:
	v_lshl_add_u64 v[8:9], v[134:135], 2, v[8:9]
	v_lshl_add_u64 v[6:7], v[68:69], 0, v[6:7]
	s_and_b64 vcc, exec, s[40:41]
	s_waitcnt vmcnt(15) lgkmcnt(0)
	v_pk_add_f32 v[2:3], v[2:3], v[222:223]
	v_pk_add_f32 v[0:1], v[0:1], v[220:221]
	global_store_dwordx4 v[6:7], v[0:3], off
	s_cbranch_vccnz .Lg1r1k3_323
	v_mul_f32_e32 v6, v1, v1
	v_fmac_f32_e32 v6, v0, v0
	v_cmp_lt_i32_e32 vcc, v185, v187
	v_fmac_f32_e32 v6, v2, v2
	v_fmac_f32_e32 v6, v3, v3
	v_cndmask_b32_e32 v7, v184, v185, vcc
	v_lshlrev_b32_e32 v7, 2, v7
	s_nop 1
	v_mov_b32_dpp v7, v6 quad_perm:[1,0,3,2] row_mask:0xf bank_mask:0xf
	v_cmp_lt_i32_e32 vcc, v188, v187
	s_waitcnt lgkmcnt(0)
	v_add_f32_e32 v8, v6, v7
	v_cndmask_b32_e32 v6, v184, v188, vcc
	v_lshlrev_b32_e32 v6, 2, v6
	s_nop 1
	v_mov_b32_dpp v9, v8 quad_perm:[2,3,0,1] row_mask:0xf bank_mask:0xf
	v_cvt_pk_bf16_f32 v6, v0, v1
	v_xor_b32_e32 v1, 4, v184
	v_cmp_lt_i32_e32 vcc, v1, v187
	v_cvt_pk_bf16_f32 v7, v2, v3
	s_waitcnt lgkmcnt(0)
	v_add_f32_e32 v0, v8, v9
	v_cndmask_b32_e32 v1, v184, v1, vcc
	v_lshlrev_b32_e32 v1, 2, v1
	s_nop 1
	v_mov_b32_dpp v1, v0 row_half_mirror row_mask:0xf bank_mask:0xf
	v_add_u32_e32 v2, 0x120, v10
	v_lshrrev_b32_e32 v3, 2, v4
	v_and_b32_e32 v2, 0x3fc, v2
	v_xor_b32_e32 v3, v3, v153
	s_waitcnt lgkmcnt(0)
	v_add_f32_e32 v0, v0, v1
	v_xor_b32_e32 v1, 8, v184
	v_cmp_lt_i32_e32 vcc, v1, v187
	v_and_or_b32 v2, v3, 3, v2
	v_lshl_or_b32 v160, v2, 4, v79
	v_cndmask_b32_e32 v1, v184, v1, vcc
	v_lshlrev_b32_e32 v1, 2, v1
	s_nop 1
	v_mov_b32_dpp v1, v0 row_mirror row_mask:0xf bank_mask:0xf
	v_lshl_add_u64 v[2:3], v[136:137], 0, v[160:161]
	global_store_dwordx2 v[2:3], v[6:7], off
	s_and_saveexec_b64 s[4:5], s[38:39]
	s_cbranch_execz .Lg1r1k3_322
	s_waitcnt lgkmcnt(0)
	v_add_f32_e32 v2, v0, v1
	v_lshl_add_u64 v[0:1], v[4:5], 2, s[24:25]
	global_atomic_add_f32 v[0:1], v2, off

; DI unsigned pk2(float lo, float hi) { f32x2 v = {lo, hi}; bfv2 b = __builtin_convertvector(v, bfv2); return __builtin_bit_cast(unsigned, b); }
; DI size_t tidxA(int row, int k) { return ((size_t)(row >> 8) * 32 + (k >> 5)) * 8192 + (size_t)(swz_chunk(row & 255, (k & 31) >> 3) * 8 + (k & 7)); }
; template <int MODE>
; DI void gemm_phase(const Params& p, int layer, unsigned char* lds) {
;     ...
;             const float* xr = layer == 0 ? (row < T_PROMPT ? p.x_prompt + (size_t)row * 1024 : p.x_sample + (size_t)(row - T_PROMPT) * 1024) : p.out + (size_t)row * 1024;
;             const f32x4 xv = *(const f32x4*)(xr + colg);
;             const f32x4 o = xv + cv;
;             *(f32x4*)(p.out + (size_t)row * 1024 + colg) = o;
;             if (layer == 0) {
;               *(u32x2*)(xb + tidxA(row, colg)) = (u32x2){pk2(o.x, o.y), pk2(o.z, o.w)};
;               float sq = o.x * o.x + o.y * o.y + o.z * o.z + o.w * o.w;
;               sq += __shfl_xor(sq, 1); sq += __shfl_xor(sq, 2); sq += __shfl_xor(sq, 4); sq += __shfl_xor(sq, 8);
;               if ((lane & 15) == 0) __hip_atomic_fetch_add(ssq + T_TOK + row, sq, __ATOMIC_RELAXED, __HIP_MEMORY_SCOPE_AGENT);
;             }
.Lg1r1k3_331:
	v_lshl_add_u64 v[8:9], v[134:135], 2, v[8:9]
	v_lshl_add_u64 v[6:7], v[68:69], 0, v[6:7]
	s_and_b64 vcc, exec, s[40:41]
	s_waitcnt vmcnt(15) lgkmcnt(0)
	v_pk_add_f32 v[2:3], v[2:3], v[230:231]
	v_pk_add_f32 v[0:1], v[0:1], v[228:229]
	global_store_dwordx4 v[6:7], v[0:3], off
	s_cbranch_vccnz .Lg1r1k3_286
	v_mul_f32_e32 v6, v1, v1
	v_fmac_f32_e32 v6, v0, v0
	v_cmp_lt_i32_e32 vcc, v185, v187
	v_fmac_f32_e32 v6, v2, v2
	v_fmac_f32_e32 v6, v3, v3
	v_cndmask_b32_e32 v7, v184, v185, vcc
	v_lshlrev_b32_e32 v7, 2, v7
	s_nop 1
	v_mov_b32_dpp v7, v6 quad_perm:[1,0,3,2] row_mask:0xf bank_mask:0xf
	v_cmp_lt_i32_e32 vcc, v188, v187
	s_waitcnt lgkmcnt(0)
	v_add_f32_e32 v8, v6, v7
	v_cndmask_b32_e32 v6, v184, v188, vcc
	v_lshlrev_b32_e32 v6, 2, v6
	s_nop 1
	v_mov_b32_dpp v9, v8 quad_perm:[2,3,0,1] row_mask:0xf bank_mask:0xf
	v_cvt_pk_bf16_f32 v6, v0, v1
	v_xor_b32_e32 v1, 4, v184
	v_cmp_lt_i32_e32 vcc, v1, v187
	v_cvt_pk_bf16_f32 v7, v2, v3
	s_waitcnt lgkmcnt(0)
	v_add_f32_e32 v0, v8, v9
	v_cndmask_b32_e32 v1, v184, v1, vcc
	v_lshlrev_b32_e32 v1, 2, v1
	s_nop 1
	v_mov_b32_dpp v1, v0 row_half_mirror row_mask:0xf bank_mask:0xf
	v_add_u32_e32 v2, 0x130, v10
	v_lshrrev_b32_e32 v3, 2, v4
	v_and_b32_e32 v2, 0x3fc, v2
	v_xor_b32_e32 v3, v3, v153
	s_waitcnt lgkmcnt(0)
	v_add_f32_e32 v0, v0, v1
	v_xor_b32_e32 v1, 8, v184
	v_cmp_lt_i32_e32 vcc, v1, v187
	v_and_or_b32 v2, v3, 3, v2
	v_lshl_or_b32 v160, v2, 4, v79
	v_cndmask_b32_e32 v1, v184, v1, vcc
	v_lshlrev_b32_e32 v1, 2, v1
	s_nop 1
	v_mov_b32_dpp v1, v0 row_mirror row_mask:0xf bank_mask:0xf
	v_lshl_add_u64 v[2:3], v[136:137], 0, v[160:161]
	global_store_dwordx2 v[2:3], v[6:7], off
	s_and_saveexec_b64 s[4:5], s[38:39]
	s_cbranch_execz .Lg1r1k3_285
	s_waitcnt lgkmcnt(0)
	v_add_f32_e32 v2, v0, v1
	v_lshl_add_u64 v[0:1], v[4:5], 2, s[24:25]
	global_atomic_add_f32 v[0:1], v2, off
	s_branch .Lg1r1k3_285
